# c16 + nt on all remaining once-read dword loads (rest of the f32 weight conversion loads, carry aggregates)
# speedup vs baseline: 1.0033x; 1.0009x over previous
; template <int KT, class F> DEVI void cvt_tile(F colptr, int ldsrc, int k0, bf16_t* out, int ldo, int v0, float* tile, int wv) {
;     ...
;     { const int vc = tid & 63, kk = tid >> 6; const float* cp = colptr(v0 + vc) + (size_t)k0 * ldsrc; float v[8 * KT];
; #pragma unroll
;       for (int r = 0; r < 8 * KT; ++r) v[r] = cp[(size_t)(r * 8 + kk) * ldsrc];
; #pragma unroll
;       for (int r = 0; r < 8 * KT; ++r) tile[vc * PITCH + r * 8 + kk] = v[r]; }
;     __syncthreads();
; DEVI void cvt_ffn_phase(const float* wg, const float* wu, const float* wd, unsigned char* ws, char* lds, int j0, int jstride, int wv) {
;     ...
;         else { const int j = job - 352, vt = j / 11, kg = j % 11; cvt_tile<4>(ColLin{wd}, DM, kg * 256, Wd, DFF, vt * 64, tile, wv); }
.LBB0_92:
	s_cmpk_gt_i32 s8, 0x15f
	s_mov_b64 s[6:7], -1
	s_cbranch_scc0 .LBB0_94
	s_add_i32 s6, s8, 0xffa0
	s_and_b32 s7, s6, 0xff
	s_mulk_i32 s7, 0x75
	s_lshr_b32 s46, s7, 8
	s_sub_i32 s46, s6, s46
	s_bfe_u32 s46, s46, 0x70001
	s_bfe_u32 s7, s7, 0x80008
	s_add_i32 s46, s46, s7
	s_bfe_u32 s7, s46, 0x50003
	s_mul_i32 s46, s7, 11
	v_mov_b32_e32 v8, v217
	s_sub_i32 s46, s6, s46
	s_lshl_b32 s6, s7, 6
	s_and_b32 s7, s46, 0xff
	v_and_b32_e32 v9, 63, v8
	v_or_b32_e32 v0, s6, v9
	v_ashrrev_i32_e32 v2, 6, v8
	v_lshlrev_b32_e32 v0, 2, v0
	v_lshl_add_u64 v[4:5], s[4:5], 0, v[0:1]
	s_lshl_b32 s46, s7, 20
	v_ashrrev_i32_e32 v3, 31, v2
	v_lshl_add_u64 v[4:5], v[4:5], 0, s[46:47]
	v_lshlrev_b64 v[6:7], 12, v[2:3]
	v_lshl_add_u64 v[4:5], v[4:5], 0, v[6:7]
	v_add_co_u32_e32 v6, vcc, s33, v4
	global_load_dword v0, v[4:5], off nt
	s_nop 0
	v_addc_co_u32_e32 v7, vcc, 0, v5, vcc
	global_load_dword v3, v[6:7], off nt
	v_add_co_u32_e32 v6, vcc, s54, v4
	s_mov_b32 s46, 0x28000
	s_nop 0
	v_addc_co_u32_e32 v7, vcc, 0, v5, vcc
	global_load_dword v10, v[6:7], off nt
	v_add_co_u32_e32 v6, vcc, s27, v4
	v_lshlrev_b32_e32 v2, 2, v2
	s_nop 0
	v_addc_co_u32_e32 v7, vcc, 0, v5, vcc
	global_load_dword v11, v[6:7], off nt
	v_add_co_u32_e32 v6, vcc, s38, v4
	s_lshl_b32 s7, s7, 9
	s_nop 0
	v_addc_co_u32_e32 v7, vcc, 0, v5, vcc
	global_load_dword v12, v[6:7], off nt
	v_add_co_u32_e32 v6, vcc, s46, v4
	s_mov_b32 s46, 0x38000
	s_nop 0
	v_addc_co_u32_e32 v7, vcc, 0, v5, vcc
	global_load_dword v13, v[6:7], off nt
	v_add_co_u32_e32 v6, vcc, s39, v4
	s_add_u32 s76, s70, s7
	s_nop 0
	v_addc_co_u32_e32 v7, vcc, 0, v5, vcc
	global_load_dword v14, v[6:7], off nt
	v_add_co_u32_e32 v6, vcc, s46, v4
	s_mov_b32 s46, 0x40000
	s_nop 0
	v_addc_co_u32_e32 v7, vcc, 0, v5, vcc
	global_load_dword v15, v[6:7], off nt
	v_add_co_u32_e32 v6, vcc, s46, v4
	s_mov_b32 s46, 0x48000
	s_nop 0
	v_addc_co_u32_e32 v7, vcc, 0, v5, vcc
	global_load_dword v16, v[6:7], off nt
	v_add_co_u32_e32 v6, vcc, s46, v4
	s_mov_b32 s46, 0x50000
	s_nop 0
	v_addc_co_u32_e32 v7, vcc, 0, v5, vcc
	global_load_dword v17, v[6:7], off nt
	v_add_co_u32_e32 v6, vcc, s46, v4
	s_mov_b32 s46, 0x58000
	s_nop 0
	v_addc_co_u32_e32 v7, vcc, 0, v5, vcc
	global_load_dword v18, v[6:7], off nt
	v_add_co_u32_e32 v6, vcc, s46, v4
	s_mov_b32 s46, 0x60000
	s_nop 0
	v_addc_co_u32_e32 v7, vcc, 0, v5, vcc
	global_load_dword v19, v[6:7], off nt
	v_add_co_u32_e32 v6, vcc, s46, v4
	s_mov_b32 s46, 0x68000
	s_nop 0
	v_addc_co_u32_e32 v7, vcc, 0, v5, vcc
	global_load_dword v20, v[6:7], off nt
	v_add_co_u32_e32 v6, vcc, s46, v4
	s_mov_b32 s46, 0x70000
	s_nop 0
	v_addc_co_u32_e32 v7, vcc, 0, v5, vcc
	global_load_dword v21, v[6:7], off nt
	v_add_co_u32_e32 v6, vcc, s46, v4
	s_mov_b32 s46, 0x78000
	s_nop 0
	v_addc_co_u32_e32 v7, vcc, 0, v5, vcc
	global_load_dword v22, v[6:7], off nt
	v_add_co_u32_e32 v6, vcc, s46, v4
	s_mov_b32 s46, 0x80000
	s_nop 0
	v_addc_co_u32_e32 v7, vcc, 0, v5, vcc
	global_load_dword v23, v[6:7], off nt
	v_add_co_u32_e32 v6, vcc, s46, v4
	s_mov_b32 s46, 0x88000
	s_nop 0
	v_addc_co_u32_e32 v7, vcc, 0, v5, vcc
	global_load_dword v24, v[6:7], off nt
	v_add_co_u32_e32 v6, vcc, s46, v4
	s_mov_b32 s46, 0x90000
	s_nop 0
	v_addc_co_u32_e32 v7, vcc, 0, v5, vcc
	global_load_dword v25, v[6:7], off nt
	v_add_co_u32_e32 v6, vcc, s46, v4
	s_mov_b32 s46, 0x98000
	s_nop 0
	v_addc_co_u32_e32 v7, vcc, 0, v5, vcc
	global_load_dword v26, v[6:7], off nt
	v_add_co_u32_e32 v6, vcc, s46, v4
	s_mov_b32 s46, 0xa0000
	s_nop 0
	v_addc_co_u32_e32 v7, vcc, 0, v5, vcc
	global_load_dword v27, v[6:7], off nt
	v_add_co_u32_e32 v6, vcc, s46, v4
	s_mov_b32 s46, 0xa8000
	s_nop 0
	v_addc_co_u32_e32 v7, vcc, 0, v5, vcc
	global_load_dword v28, v[6:7], off nt
	v_add_co_u32_e32 v6, vcc, s46, v4
	s_mov_b32 s46, 0xb0000
	s_nop 0
	v_addc_co_u32_e32 v7, vcc, 0, v5, vcc
	global_load_dword v29, v[6:7], off nt
	v_add_co_u32_e32 v6, vcc, s46, v4
	s_mov_b32 s46, 0xb8000
	s_nop 0
	v_addc_co_u32_e32 v7, vcc, 0, v5, vcc
	global_load_dword v30, v[6:7], off nt
	v_add_co_u32_e32 v6, vcc, s46, v4
	s_mov_b32 s46, 0xc0000
	s_nop 0
	v_addc_co_u32_e32 v7, vcc, 0, v5, vcc
	global_load_dword v31, v[6:7], off nt
	v_add_co_u32_e32 v6, vcc, s46, v4
	s_mov_b32 s46, 0xc8000
	s_nop 0
	v_addc_co_u32_e32 v7, vcc, 0, v5, vcc
	global_load_dword v32, v[6:7], off nt
	v_add_co_u32_e32 v6, vcc, s46, v4
	s_mov_b32 s46, 0xd0000
	s_nop 0
	v_addc_co_u32_e32 v7, vcc, 0, v5, vcc
	global_load_dword v33, v[6:7], off nt
	v_add_co_u32_e32 v6, vcc, s46, v4
	s_mov_b32 s46, 0xd8000
	s_nop 0
	v_addc_co_u32_e32 v7, vcc, 0, v5, vcc
	global_load_dword v34, v[6:7], off nt
	v_add_co_u32_e32 v6, vcc, s46, v4
	s_mov_b32 s46, 0xe0000
	s_nop 0
	v_addc_co_u32_e32 v7, vcc, 0, v5, vcc
	global_load_dword v35, v[6:7], off nt
	v_add_co_u32_e32 v6, vcc, s46, v4
	s_mov_b32 s46, 0xe8000
	s_nop 0
	v_addc_co_u32_e32 v7, vcc, 0, v5, vcc
	global_load_dword v36, v[6:7], off nt
	v_add_co_u32_e32 v6, vcc, s46, v4
	s_mov_b32 s46, 0xf0000
	s_nop 0
	v_addc_co_u32_e32 v7, vcc, 0, v5, vcc
	global_load_dword v37, v[6:7], off nt
	v_add_co_u32_e32 v6, vcc, s46, v4
	s_mov_b32 s46, 0xf8000
	s_nop 0
	v_addc_co_u32_e32 v7, vcc, 0, v5, vcc
	v_add_co_u32_e32 v4, vcc, s46, v4
	global_load_dword v6, v[6:7], off nt
	s_nop 0
	v_addc_co_u32_e32 v5, vcc, 0, v5, vcc
	global_load_dword v4, v[4:5], off nt
	v_mul_u32_u24_e32 v5, 0x404, v9
	v_add3_u32 v2, 0, v5, v2
	v_add_u32_e32 v2, 0x8000, v2
	s_waitcnt vmcnt(0)
	ds_write2_b32 v2, v0, v3 offset1:8
	ds_write2_b32 v2, v10, v11 offset0:16 offset1:24
	ds_write2_b32 v2, v12, v13 offset0:32 offset1:40
	ds_write2_b32 v2, v14, v15 offset0:48 offset1:56
	ds_write2_b32 v2, v16, v17 offset0:64 offset1:72
	ds_write2_b32 v2, v18, v19 offset0:80 offset1:88
	ds_write2_b32 v2, v20, v21 offset0:96 offset1:104
	ds_write2_b32 v2, v22, v23 offset0:112 offset1:120
	ds_write2_b32 v2, v24, v25 offset0:128 offset1:136
	ds_write2_b32 v2, v26, v27 offset0:144 offset1:152
	ds_write2_b32 v2, v28, v29 offset0:160 offset1:168
	ds_write2_b32 v2, v30, v31 offset0:176 offset1:184
	ds_write2_b32 v2, v32, v33 offset0:192 offset1:200
	ds_write2_b32 v2, v34, v35 offset0:208 offset1:216
	ds_write2_b32 v2, v36, v37 offset0:224 offset1:232
	ds_write2_b32 v2, v6, v4 offset0:240 offset1:248
	v_lshlrev_b32_e32 v2, 3, v8
	v_ashrrev_i32_e32 v0, 3, v8
	v_and_b32_e32 v4, 56, v2
	v_mul_lo_u32 v2, v0, s43
	v_lshlrev_b32_e32 v3, 2, v4
	s_addc_u32 s77, s71, 0
	v_add3_u32 v10, 0, v2, v3
	v_add_u32_e32 v0, s6, v0
	v_mov_b64_e32 v[2:3], s[76:77]
	v_add_u32_e32 v5, 0x8000, v10
	v_mad_i64_i32 v[2:3], s[6:7], v0, s3, v[2:3]
	v_lshlrev_b32_e32 v0, 1, v4
	s_waitcnt lgkmcnt(0)
	s_barrier
; DEVI unsigned cvtpk(float lo, float hi) { unsigned r; asm volatile("v_cvt_pk_bf16_f32 %0, %1, %2" : "=v"(r) : "v"(lo), "v"(hi)); return r; }
; template <int KT, class F> DEVI void cvt_tile(F colptr, int ldsrc, int k0, bf16_t* out, int ldo, int v0, float* tile, int wv) {
;     ...
;     { const int vc = tid >> 3, k8 = (tid & 7) * 8;
; #pragma unroll
;       for (int q = 0; q < KT; ++q) { const float* tp = tile + vc * PITCH + q * 64 + k8;
;         u32x4 w = {cvtpk(tp[0], tp[1]), cvtpk(tp[2], tp[3]), cvtpk(tp[4], tp[5]), cvtpk(tp[6], tp[7])};
;         *(u32x4*)(out + (size_t)(v0 + vc) * ldo + k0 + q * 64 + k8) = w; } }
;     __syncthreads();
	v_lshl_add_u64 v[6:7], v[2:3], 0, v[0:1]
	ds_read2_b32 v[2:3], v5 offset1:1
	v_add_u32_e32 v0, 0x8008, v10
	s_waitcnt lgkmcnt(0)
	v_cvt_pk_bf16_f32 v2, v2, v3
	ds_read2_b32 v[4:5], v0 offset1:1
	v_add_u32_e32 v0, 0x8010, v10
	s_waitcnt lgkmcnt(0)
	v_cvt_pk_bf16_f32 v3, v4, v5
	ds_read2_b32 v[4:5], v0 offset1:1
	v_add_u32_e32 v0, 0x8018, v10
	s_waitcnt lgkmcnt(0)
	v_cvt_pk_bf16_f32 v4, v4, v5
	ds_read2_b32 v[8:9], v0 offset1:1
	s_waitcnt lgkmcnt(0)
	v_cvt_pk_bf16_f32 v5, v8, v9
	flat_store_dwordx4 v[6:7], v[2:5]
	v_add_u32_e32 v0, 0x8100, v10
	ds_read2_b32 v[2:3], v0 offset1:1
	v_add_u32_e32 v0, 0x8108, v10
	s_waitcnt lgkmcnt(0)
	v_cvt_pk_bf16_f32 v2, v2, v3
	ds_read2_b32 v[4:5], v0 offset1:1
	v_add_u32_e32 v0, 0x8110, v10
	s_waitcnt lgkmcnt(0)
	v_cvt_pk_bf16_f32 v3, v4, v5
	ds_read2_b32 v[4:5], v0 offset1:1
	v_add_u32_e32 v0, 0x8118, v10
	s_waitcnt lgkmcnt(0)
	v_cvt_pk_bf16_f32 v4, v4, v5
	ds_read2_b32 v[8:9], v0 offset1:1
	s_waitcnt lgkmcnt(0)
	v_cvt_pk_bf16_f32 v5, v8, v9
	flat_store_dwordx4 v[6:7], v[2:5] offset:128
	v_add_u32_e32 v0, 0x8200, v10
	ds_read2_b32 v[2:3], v0 offset1:1
	v_add_u32_e32 v0, 0x8208, v10
	s_waitcnt lgkmcnt(0)
	v_cvt_pk_bf16_f32 v2, v2, v3
	ds_read2_b32 v[4:5], v0 offset1:1
	v_add_u32_e32 v0, 0x8210, v10
	s_waitcnt lgkmcnt(0)
	v_cvt_pk_bf16_f32 v3, v4, v5
	ds_read2_b32 v[4:5], v0 offset1:1
	v_add_u32_e32 v0, 0x8218, v10
	s_waitcnt lgkmcnt(0)
	v_cvt_pk_bf16_f32 v4, v4, v5
	ds_read2_b32 v[8:9], v0 offset1:1
	s_waitcnt lgkmcnt(0)
	v_cvt_pk_bf16_f32 v5, v8, v9
	flat_store_dwordx4 v[6:7], v[2:5] offset:256
	v_add_u32_e32 v0, 0x8300, v10
	ds_read2_b32 v[2:3], v0 offset1:1
	v_add_u32_e32 v0, 0x8308, v10
	s_waitcnt lgkmcnt(0)
	v_cvt_pk_bf16_f32 v2, v2, v3
	ds_read2_b32 v[4:5], v0 offset1:1
	v_add_u32_e32 v0, 0x8310, v10
	s_waitcnt lgkmcnt(0)
	v_cvt_pk_bf16_f32 v3, v4, v5
	ds_read2_b32 v[4:5], v0 offset1:1
	v_add_u32_e32 v0, 0x8318, v10
	s_waitcnt lgkmcnt(0)
	v_cvt_pk_bf16_f32 v4, v4, v5
	ds_read2_b32 v[8:9], v0 offset1:1
	s_waitcnt lgkmcnt(0)
	v_cvt_pk_bf16_f32 v5, v8, v9
	flat_store_dwordx4 v[6:7], v[2:5] offset:384
	s_waitcnt lgkmcnt(0)
	s_barrier
	s_mov_b64 s[6:7], 0

; template <int KT, class F> DEVI void cvt_tile(F colptr, int ldsrc, int k0, bf16_t* out, int ldo, int v0, float* tile, int wv) {
;     ...
;     { const int vc = tid & 63, kk = tid >> 6; const float* cp = colptr(v0 + vc) + (size_t)k0 * ldsrc; float v[8 * KT];
; #pragma unroll
;       for (int r = 0; r < 8 * KT; ++r) v[r] = cp[(size_t)(r * 8 + kk) * ldsrc];
; #pragma unroll
;       for (int r = 0; r < 8 * KT; ++r) tile[vc * PITCH + r * 8 + kk] = v[r]; }
;     __syncthreads();
; DEVI void cvt_ffn_phase(const float* wg, const float* wu, const float* wd, unsigned char* ws, char* lds, int j0, int jstride, int wv) {
;     ...
;         else { const int j = job - 352, vt = j / 11, kg = j % 11; cvt_tile<4>(ColLin{wd}, DM, kg * 256, Wd, DFF, vt * 64, tile, wv); }
.LBB0_100:
	s_cmpk_gt_i32 s60, 0x15f
	s_mov_b64 s[6:7], -1
	s_cbranch_scc0 .LBB0_102
	s_add_i32 s6, s60, 0xffa0
	s_and_b32 s7, s6, 0xff
	s_mulk_i32 s7, 0x75
	s_lshr_b32 s46, s7, 8
	s_sub_i32 s46, s6, s46
	s_bfe_u32 s46, s46, 0x70001
	s_bfe_u32 s7, s7, 0x80008
	s_add_i32 s46, s46, s7
	s_bfe_u32 s7, s46, 0x50003
	s_mul_i32 s46, s7, 11
	v_mov_b32_e32 v8, v217
	s_sub_i32 s46, s6, s46
	s_lshl_b32 s6, s7, 6
	s_and_b32 s7, s46, 0xff
	v_and_b32_e32 v9, 63, v8
	v_or_b32_e32 v0, s6, v9
	v_ashrrev_i32_e32 v2, 6, v8
	v_lshlrev_b32_e32 v0, 2, v0
	v_lshl_add_u64 v[4:5], s[4:5], 0, v[0:1]
	s_lshl_b32 s46, s7, 20
	v_ashrrev_i32_e32 v3, 31, v2
	v_lshl_add_u64 v[4:5], v[4:5], 0, s[46:47]
	v_lshlrev_b64 v[6:7], 12, v[2:3]
	v_lshl_add_u64 v[4:5], v[4:5], 0, v[6:7]
	v_add_co_u32_e32 v6, vcc, s33, v4
	global_load_dword v0, v[4:5], off nt
	s_nop 0
	v_addc_co_u32_e32 v7, vcc, 0, v5, vcc
	global_load_dword v3, v[6:7], off nt
	v_add_co_u32_e32 v6, vcc, s54, v4
	s_mov_b32 s46, 0x28000
	s_nop 0
	v_addc_co_u32_e32 v7, vcc, 0, v5, vcc
	global_load_dword v10, v[6:7], off nt
	v_add_co_u32_e32 v6, vcc, s27, v4
	v_lshlrev_b32_e32 v2, 2, v2
	s_nop 0
	v_addc_co_u32_e32 v7, vcc, 0, v5, vcc
	global_load_dword v11, v[6:7], off nt
	v_add_co_u32_e32 v6, vcc, s38, v4
	s_lshl_b32 s7, s7, 9
	s_nop 0
	v_addc_co_u32_e32 v7, vcc, 0, v5, vcc
	global_load_dword v12, v[6:7], off nt
	v_add_co_u32_e32 v6, vcc, s46, v4
	s_mov_b32 s46, 0x38000
	s_nop 0
	v_addc_co_u32_e32 v7, vcc, 0, v5, vcc
	global_load_dword v13, v[6:7], off nt
	v_add_co_u32_e32 v6, vcc, s39, v4
	s_add_u32 s76, s70, s7
	s_nop 0
	v_addc_co_u32_e32 v7, vcc, 0, v5, vcc
	global_load_dword v14, v[6:7], off nt
	v_add_co_u32_e32 v6, vcc, s46, v4
	s_mov_b32 s46, 0x40000
	s_nop 0
	v_addc_co_u32_e32 v7, vcc, 0, v5, vcc
	global_load_dword v15, v[6:7], off nt
	v_add_co_u32_e32 v6, vcc, s46, v4
	s_mov_b32 s46, 0x48000
	s_nop 0
	v_addc_co_u32_e32 v7, vcc, 0, v5, vcc
	global_load_dword v16, v[6:7], off nt
	v_add_co_u32_e32 v6, vcc, s46, v4
	s_mov_b32 s46, 0x50000
	s_nop 0
	v_addc_co_u32_e32 v7, vcc, 0, v5, vcc
	global_load_dword v17, v[6:7], off nt
	v_add_co_u32_e32 v6, vcc, s46, v4
	s_mov_b32 s46, 0x58000
	s_nop 0
	v_addc_co_u32_e32 v7, vcc, 0, v5, vcc
	global_load_dword v18, v[6:7], off nt
	v_add_co_u32_e32 v6, vcc, s46, v4
	s_mov_b32 s46, 0x60000
	s_nop 0
	v_addc_co_u32_e32 v7, vcc, 0, v5, vcc
	global_load_dword v19, v[6:7], off nt
	v_add_co_u32_e32 v6, vcc, s46, v4
	s_mov_b32 s46, 0x68000
	s_nop 0
	v_addc_co_u32_e32 v7, vcc, 0, v5, vcc
	global_load_dword v20, v[6:7], off nt
	v_add_co_u32_e32 v6, vcc, s46, v4
	s_mov_b32 s46, 0x70000
	s_nop 0
	v_addc_co_u32_e32 v7, vcc, 0, v5, vcc
	global_load_dword v21, v[6:7], off nt
	v_add_co_u32_e32 v6, vcc, s46, v4
	s_mov_b32 s46, 0x78000
	s_nop 0
	v_addc_co_u32_e32 v7, vcc, 0, v5, vcc
	global_load_dword v22, v[6:7], off nt
	v_add_co_u32_e32 v6, vcc, s46, v4
	s_mov_b32 s46, 0x80000
	s_nop 0
	v_addc_co_u32_e32 v7, vcc, 0, v5, vcc
	global_load_dword v23, v[6:7], off nt
	v_add_co_u32_e32 v6, vcc, s46, v4
	s_mov_b32 s46, 0x88000
	s_nop 0
	v_addc_co_u32_e32 v7, vcc, 0, v5, vcc
	global_load_dword v24, v[6:7], off nt
	v_add_co_u32_e32 v6, vcc, s46, v4
	s_mov_b32 s46, 0x90000
	s_nop 0
	v_addc_co_u32_e32 v7, vcc, 0, v5, vcc
	global_load_dword v25, v[6:7], off nt
	v_add_co_u32_e32 v6, vcc, s46, v4
	s_mov_b32 s46, 0x98000
	s_nop 0
	v_addc_co_u32_e32 v7, vcc, 0, v5, vcc
	global_load_dword v26, v[6:7], off nt
	v_add_co_u32_e32 v6, vcc, s46, v4
	s_mov_b32 s46, 0xa0000
	s_nop 0
	v_addc_co_u32_e32 v7, vcc, 0, v5, vcc
	global_load_dword v27, v[6:7], off nt
	v_add_co_u32_e32 v6, vcc, s46, v4
	s_mov_b32 s46, 0xa8000
	s_nop 0
	v_addc_co_u32_e32 v7, vcc, 0, v5, vcc
	global_load_dword v28, v[6:7], off nt
	v_add_co_u32_e32 v6, vcc, s46, v4
	s_mov_b32 s46, 0xb0000
	s_nop 0
	v_addc_co_u32_e32 v7, vcc, 0, v5, vcc
	global_load_dword v29, v[6:7], off nt
	v_add_co_u32_e32 v6, vcc, s46, v4
	s_mov_b32 s46, 0xb8000
	s_nop 0
	v_addc_co_u32_e32 v7, vcc, 0, v5, vcc
	global_load_dword v30, v[6:7], off nt
	v_add_co_u32_e32 v6, vcc, s46, v4
	s_mov_b32 s46, 0xc0000
	s_nop 0
	v_addc_co_u32_e32 v7, vcc, 0, v5, vcc
	global_load_dword v31, v[6:7], off nt
	v_add_co_u32_e32 v6, vcc, s46, v4
	s_mov_b32 s46, 0xc8000
	s_nop 0
	v_addc_co_u32_e32 v7, vcc, 0, v5, vcc
	global_load_dword v32, v[6:7], off nt
	v_add_co_u32_e32 v6, vcc, s46, v4
	s_mov_b32 s46, 0xd0000
	s_nop 0
	v_addc_co_u32_e32 v7, vcc, 0, v5, vcc
	global_load_dword v33, v[6:7], off nt
	v_add_co_u32_e32 v6, vcc, s46, v4
	s_mov_b32 s46, 0xd8000
	s_nop 0
	v_addc_co_u32_e32 v7, vcc, 0, v5, vcc
	global_load_dword v34, v[6:7], off nt
	v_add_co_u32_e32 v6, vcc, s46, v4
	s_mov_b32 s46, 0xe0000
	s_nop 0
	v_addc_co_u32_e32 v7, vcc, 0, v5, vcc
	global_load_dword v35, v[6:7], off nt
	v_add_co_u32_e32 v6, vcc, s46, v4
	s_mov_b32 s46, 0xe8000
	s_nop 0
	v_addc_co_u32_e32 v7, vcc, 0, v5, vcc
	global_load_dword v36, v[6:7], off nt
	v_add_co_u32_e32 v6, vcc, s46, v4
	s_mov_b32 s46, 0xf0000
	s_nop 0
	v_addc_co_u32_e32 v7, vcc, 0, v5, vcc
	global_load_dword v37, v[6:7], off nt
	v_add_co_u32_e32 v6, vcc, s46, v4
	s_mov_b32 s46, 0xf8000
	s_nop 0
	v_addc_co_u32_e32 v7, vcc, 0, v5, vcc
	v_add_co_u32_e32 v4, vcc, s46, v4
	global_load_dword v6, v[6:7], off nt
	s_nop 0
	v_addc_co_u32_e32 v5, vcc, 0, v5, vcc
	global_load_dword v4, v[4:5], off nt
	v_mul_u32_u24_e32 v5, 0x404, v9
	v_add3_u32 v2, 0, v5, v2
	v_add_u32_e32 v2, 0x8000, v2
	s_waitcnt vmcnt(0)
	ds_write2_b32 v2, v0, v3 offset1:8
	ds_write2_b32 v2, v10, v11 offset0:16 offset1:24
	ds_write2_b32 v2, v12, v13 offset0:32 offset1:40
	ds_write2_b32 v2, v14, v15 offset0:48 offset1:56
	ds_write2_b32 v2, v16, v17 offset0:64 offset1:72
	ds_write2_b32 v2, v18, v19 offset0:80 offset1:88
	ds_write2_b32 v2, v20, v21 offset0:96 offset1:104
	ds_write2_b32 v2, v22, v23 offset0:112 offset1:120
	ds_write2_b32 v2, v24, v25 offset0:128 offset1:136
	ds_write2_b32 v2, v26, v27 offset0:144 offset1:152
	ds_write2_b32 v2, v28, v29 offset0:160 offset1:168
	ds_write2_b32 v2, v30, v31 offset0:176 offset1:184
	ds_write2_b32 v2, v32, v33 offset0:192 offset1:200
	ds_write2_b32 v2, v34, v35 offset0:208 offset1:216
	ds_write2_b32 v2, v36, v37 offset0:224 offset1:232
	ds_write2_b32 v2, v6, v4 offset0:240 offset1:248
	v_lshlrev_b32_e32 v2, 3, v8
	v_ashrrev_i32_e32 v0, 3, v8
	v_and_b32_e32 v4, 56, v2
	v_mul_lo_u32 v2, v0, s43
	v_lshlrev_b32_e32 v3, 2, v4
	s_addc_u32 s77, s71, 0
	v_add3_u32 v10, 0, v2, v3
	v_add_u32_e32 v0, s6, v0
	v_mov_b64_e32 v[2:3], s[76:77]
	v_add_u32_e32 v5, 0x8000, v10
	v_mad_i64_i32 v[2:3], s[6:7], v0, s3, v[2:3]
	v_lshlrev_b32_e32 v0, 1, v4
	s_waitcnt lgkmcnt(0)
	s_barrier
; DEVI unsigned cvtpk(float lo, float hi) { unsigned r; asm volatile("v_cvt_pk_bf16_f32 %0, %1, %2" : "=v"(r) : "v"(lo), "v"(hi)); return r; }
; template <int KT, class F> DEVI void cvt_tile(F colptr, int ldsrc, int k0, bf16_t* out, int ldo, int v0, float* tile, int wv) {
;     ...
;     { const int vc = tid >> 3, k8 = (tid & 7) * 8;
; #pragma unroll
;       for (int q = 0; q < KT; ++q) { const float* tp = tile + vc * PITCH + q * 64 + k8;
;         u32x4 w = {cvtpk(tp[0], tp[1]), cvtpk(tp[2], tp[3]), cvtpk(tp[4], tp[5]), cvtpk(tp[6], tp[7])};
;         *(u32x4*)(out + (size_t)(v0 + vc) * ldo + k0 + q * 64 + k8) = w; } }
;     __syncthreads();
	v_lshl_add_u64 v[6:7], v[2:3], 0, v[0:1]
	ds_read2_b32 v[2:3], v5 offset1:1
	v_add_u32_e32 v0, 0x8008, v10
	s_waitcnt lgkmcnt(0)
	v_cvt_pk_bf16_f32 v2, v2, v3
	ds_read2_b32 v[4:5], v0 offset1:1
	v_add_u32_e32 v0, 0x8010, v10
	s_waitcnt lgkmcnt(0)
	v_cvt_pk_bf16_f32 v3, v4, v5
	ds_read2_b32 v[4:5], v0 offset1:1
	v_add_u32_e32 v0, 0x8018, v10
	s_waitcnt lgkmcnt(0)
	v_cvt_pk_bf16_f32 v4, v4, v5
	ds_read2_b32 v[8:9], v0 offset1:1
	s_waitcnt lgkmcnt(0)
	v_cvt_pk_bf16_f32 v5, v8, v9
	flat_store_dwordx4 v[6:7], v[2:5]
	v_add_u32_e32 v0, 0x8100, v10
	ds_read2_b32 v[2:3], v0 offset1:1
	v_add_u32_e32 v0, 0x8108, v10
	s_waitcnt lgkmcnt(0)
	v_cvt_pk_bf16_f32 v2, v2, v3
	ds_read2_b32 v[4:5], v0 offset1:1
	v_add_u32_e32 v0, 0x8110, v10
	s_waitcnt lgkmcnt(0)
	v_cvt_pk_bf16_f32 v3, v4, v5
	ds_read2_b32 v[4:5], v0 offset1:1
	v_add_u32_e32 v0, 0x8118, v10
	s_waitcnt lgkmcnt(0)
	v_cvt_pk_bf16_f32 v4, v4, v5
	ds_read2_b32 v[8:9], v0 offset1:1
	s_waitcnt lgkmcnt(0)
	v_cvt_pk_bf16_f32 v5, v8, v9
	flat_store_dwordx4 v[6:7], v[2:5] offset:128
	v_add_u32_e32 v0, 0x8200, v10
	ds_read2_b32 v[2:3], v0 offset1:1
	v_add_u32_e32 v0, 0x8208, v10
	s_waitcnt lgkmcnt(0)
	v_cvt_pk_bf16_f32 v2, v2, v3
	ds_read2_b32 v[4:5], v0 offset1:1
	v_add_u32_e32 v0, 0x8210, v10
	s_waitcnt lgkmcnt(0)
	v_cvt_pk_bf16_f32 v3, v4, v5
	ds_read2_b32 v[4:5], v0 offset1:1
	v_add_u32_e32 v0, 0x8218, v10
	s_waitcnt lgkmcnt(0)
	v_cvt_pk_bf16_f32 v4, v4, v5
	ds_read2_b32 v[8:9], v0 offset1:1
	s_waitcnt lgkmcnt(0)
	v_cvt_pk_bf16_f32 v5, v8, v9
	flat_store_dwordx4 v[6:7], v[2:5] offset:256
	v_add_u32_e32 v0, 0x8300, v10
	ds_read2_b32 v[2:3], v0 offset1:1
	v_add_u32_e32 v0, 0x8308, v10
	s_waitcnt lgkmcnt(0)
	v_cvt_pk_bf16_f32 v2, v2, v3
	ds_read2_b32 v[4:5], v0 offset1:1
	v_add_u32_e32 v0, 0x8310, v10
	s_waitcnt lgkmcnt(0)
	v_cvt_pk_bf16_f32 v3, v4, v5
	ds_read2_b32 v[4:5], v0 offset1:1
	v_add_u32_e32 v0, 0x8318, v10
	s_waitcnt lgkmcnt(0)
	v_cvt_pk_bf16_f32 v4, v4, v5
	ds_read2_b32 v[8:9], v0 offset1:1
	s_waitcnt lgkmcnt(0)
	v_cvt_pk_bf16_f32 v5, v8, v9
	flat_store_dwordx4 v[6:7], v[2:5] offset:384
	s_waitcnt lgkmcnt(0)
	s_barrier
	s_mov_b64 s[6:7], 0

; DEVI void rnn_local_phase(const bf16_t* xr, const float* convw, const float* convb, const bf16_t* lruT, const float* ba, const float* bx, const float* lam,
;                           bf16_t* hloc, bf16_t* pcum, float* aggA, float* aggH, char* lds, int wv) {
;     ...
;     if (tid < 320) cwL[tid] = tid < 256 ? convw[(tid >> 6) * 1024 + ch0 + (tid & 63)] : convb[ch0 + (tid & 63)];
.LBB0_113:
	s_waitcnt lgkmcnt(0)
	s_andn2_saveexec_b64 s[10:11], s[60:61]
	s_lshl_b32 s60, s12, 12
	s_ashr_i32 s61, s60, 31
	s_lshl_b64 s[60:61], s[60:61], 2
	v_lshlrev_b32_e32 v0, 10, v0
	s_add_u32 s8, s8, s60
	v_or3_b32 v2, s77, v0, v4
	s_addc_u32 s9, s9, s61
	v_ashrrev_i32_e32 v3, 31, v2
	v_lshl_add_u64 v[2:3], v[2:3], 2, s[8:9]
	s_or_b64 exec, exec, s[10:11]
	global_load_dword v0, v[2:3], off nt
	v_lshl_add_u32 v2, v7, 2, 0
	v_add_u32_e32 v2, 0x1de00, v2
	s_waitcnt vmcnt(0)
	ds_write_b32 v2, v0

; DEVI unsigned cvtpk(float lo, float hi) { unsigned r; asm volatile("v_cvt_pk_bf16_f32 %0, %1, %2" : "=v"(r) : "v"(lo), "v"(hi)); return r; }
; DEVI int ltid(int wv) { int t = (wv << 6) | (int)__builtin_amdgcn_mbcnt_hi(~0u, __builtin_amdgcn_mbcnt_lo(~0u, 0u)); asm volatile("" : "+v"(t)); return t; }
; DEVI int lbid() { int t = blockIdx.x; asm volatile("" : "+s"(t)); return t; }
; template <int KT, class F> DEVI void cvt_tile(F colptr, int ldsrc, int k0, bf16_t* out, int ldo, int v0, float* tile, int wv) {
;     const int tid = ltid(wv);
;     constexpr int PITCH = KT * 64 + 1;
;     { const int vc = tid & 63, kk = tid >> 6; const float* cp = colptr(v0 + vc) + (size_t)k0 * ldsrc; float v[8 * KT];
; #pragma unroll
;       for (int r = 0; r < 8 * KT; ++r) v[r] = cp[(size_t)(r * 8 + kk) * ldsrc];
; #pragma unroll
;       for (int r = 0; r < 8 * KT; ++r) tile[vc * PITCH + r * 8 + kk] = v[r]; }
;     __syncthreads();
;     { const int vc = tid >> 3, k8 = (tid & 7) * 8;
; #pragma unroll
;       for (int q = 0; q < KT; ++q) { const float* tp = tile + vc * PITCH + q * 64 + k8;
;         u32x4 w = {cvtpk(tp[0], tp[1]), cvtpk(tp[2], tp[3]), cvtpk(tp[4], tp[5]), cvtpk(tp[6], tp[7])};
;         *(u32x4*)(out + (size_t)(v0 + vc) * ldo + k0 + q * 64 + k8) = w; } }
;     __syncthreads();
; }
; DEVI void cvt_mix_phase(const float* win, const float* woa, const float* wor, const float* wout, const float* lwa, const float* lwx, unsigned char* ws, char* lds, int wv) {
;     float* tile = (float*)(lds + 32768);
;     for (int job = lbid(); job < 448 + 192 + 32; job += lgrid()) {
;         if (job < 448) { const int vt = job >> 2, kg = job & 3; cvt_tile<4>(ColIn{win}, NIN, kg * 256, (bf16_t*)(ws + WS_WIN), DM, vt * 64, tile, wv); }
;         else if (job < 448 + 192) { const int j = job - 448, m = j >> 6, jj = j & 63, vt = jj >> 2, kg = jj & 3;
;             const float* src = m == 0 ? woa : (m == 1 ? wor : wout);
;             if (m < 2) cvt_tile<4>(ColLin{src}, DM, kg * 256, (bf16_t*)(ws + WS_WOA) + m * DM, 2 * DM, vt * 64, tile, wv);
;             else cvt_tile<4>(ColLin{src}, DM, kg * 256, (bf16_t*)(ws + WS_WOUT), DM, vt * 64, tile, wv); }
;         else { const int j = job - 448 - 192, gate = j >> 4, n = j & 15; const float* src = (gate ? lwx : lwa) + n * 4096;
;             cvt_tile<1>(ColLin{src}, 64, 0, (bf16_t*)(ws + WS_LRU) + n * 8192 + gate * 4096, 64, 0, tile, wv); }
.LBB0_451:
	s_cmpk_gt_i32 s59, 0x1bf
	s_mov_b64 s[22:23], -1
	s_cbranch_scc0 .LBB0_460
	s_cmpk_gt_u32 s59, 0x27f
	s_cbranch_scc0 .LBB0_454
	s_add_i32 s24, s59, 0xfffffd80
	s_and_b32 s22, s59, 15
	s_cmp_lt_u32 s24, 16
	s_cselect_b32 s25, s16, s18
	s_cselect_b32 s23, s17, s19
	s_add_u32 s25, s25, s4
	s_addc_u32 s23, s23, s5
	s_lshl_b32 s46, s22, 14
	v_mov_b32_e32 v12, v217
	s_add_u32 s22, s25, s46
	s_addc_u32 s23, s23, 0
	v_and_b32_e32 v13, 63, v12
	v_ashrrev_i32_e32 v2, 6, v12
	v_lshlrev_b32_e32 v0, 2, v13
	v_ashrrev_i32_e32 v3, 31, v2
	v_lshl_add_u64 v[4:5], s[22:23], 0, v[0:1]
	v_lshlrev_b64 v[6:7], 8, v[2:3]
	v_lshl_add_u64 v[4:5], v[4:5], 0, v[6:7]
	s_movk_i32 s22, 0x1000
	v_add_co_u32_e32 v6, vcc, s22, v4
	s_movk_i32 s22, 0x2000
	s_nop 0
	v_addc_co_u32_e32 v7, vcc, 0, v5, vcc
	v_add_co_u32_e32 v8, vcc, s22, v4
	s_movk_i32 s22, 0x3000
	s_nop 0
	v_addc_co_u32_e32 v9, vcc, 0, v5, vcc
	v_add_co_u32_e32 v10, vcc, s22, v4
	s_movk_i32 s22, 0x104
	s_nop 0
	v_addc_co_u32_e32 v11, vcc, 0, v5, vcc
	global_load_dword v0, v[4:5], off nt
	global_load_dword v3, v[4:5], off offset:2048
	s_nop 0
	global_load_dword v5, v[8:9], off offset:-4096
	s_nop 0
	global_load_dword v6, v[6:7], off offset:2048
	s_nop 0
	global_load_dword v7, v[8:9], off nt
	s_nop 0
	global_load_dword v8, v[8:9], off offset:2048
	s_nop 0
	global_load_dword v9, v[10:11], off nt
	s_nop 0
	global_load_dword v10, v[10:11], off offset:2048
	v_ashrrev_i32_e32 v4, 3, v12
	v_lshlrev_b32_e32 v11, 3, v12
	v_mul_u32_u24_e32 v12, 0x104, v13
	v_lshlrev_b32_e32 v2, 2, v2
	v_and_b32_e32 v11, 56, v11
	v_mul_lo_u32 v13, v4, s22
	v_readlane_b32 s22, v255, 29
	v_add3_u32 v2, 0, v12, v2
	v_lshlrev_b32_e32 v12, 2, v11
	s_add_u32 s22, s22, s46
	v_readlane_b32 s23, v255, 30
	v_add3_u32 v12, 0, v12, v13
	s_addc_u32 s23, s23, 0
	s_lshl_b32 s24, s24, 9
	v_add_u32_e32 v2, 0x8000, v2
	v_add_u32_e32 v13, 0x8000, v12
	s_and_b32 s24, s24, 0xffffe000
	s_add_u32 s22, s22, s24
	s_addc_u32 s23, s23, 0
	s_waitcnt vmcnt(0)
	ds_write2_b32 v2, v0, v3 offset1:8
	ds_write2_b32 v2, v5, v6 offset0:16 offset1:24
	ds_write2_b32 v2, v7, v8 offset0:32 offset1:40
	ds_write2_b32 v2, v9, v10 offset0:48 offset1:56
	s_waitcnt lgkmcnt(0)
	s_barrier
	ds_read2_b32 v[2:3], v13 offset1:1
	v_ashrrev_i32_e32 v5, 31, v4
	v_add_u32_e32 v0, 0x8008, v12
	s_waitcnt lgkmcnt(0)
	v_cvt_pk_bf16_f32 v2, v2, v3
	ds_read2_b32 v[6:7], v0 offset1:1
	v_lshlrev_b64 v[8:9], 7, v[4:5]
	v_add_u32_e32 v0, 0x8010, v12
	s_waitcnt lgkmcnt(0)
	v_cvt_pk_bf16_f32 v3, v6, v7
	ds_read2_b32 v[4:5], v0 offset1:1
	v_lshlrev_b32_e32 v0, 1, v11
	v_lshl_add_u64 v[8:9], s[22:23], 0, v[8:9]
	v_add_u32_e32 v10, 0x8018, v12
	v_lshl_add_u64 v[8:9], v[8:9], 0, v[0:1]
	s_waitcnt lgkmcnt(0)
	v_cvt_pk_bf16_f32 v4, v4, v5
	ds_read2_b32 v[6:7], v10 offset1:1
	s_waitcnt lgkmcnt(0)
	v_cvt_pk_bf16_f32 v5, v6, v7
	flat_store_dwordx4 v[8:9], v[2:5]
	s_waitcnt lgkmcnt(0)
	s_barrier
	s_mov_b64 s[22:23], 0
.LBB0_454:
	s_andn2_b64 vcc, exec, s[22:23]
	s_cbranch_vccnz .LBB0_459
	s_add_i32 s80, s59, 0xfffffe40
	s_lshr_b32 s79, s80, 6
	s_bfe_u32 s78, s59, 0x40002
	s_and_b32 s76, s59, 3
	s_cmp_eq_u32 s79, 1
	s_cselect_b32 s22, s6, s20
	s_cselect_b32 s23, s7, s21
	s_add_u32 s22, s22, s12
	s_addc_u32 s23, s23, s13
	s_cmpk_gt_u32 s80, 0x7f
	s_mov_b64 s[24:25], -1
	s_cbranch_scc0 .LBB0_457
	v_mov_b32_e32 v8, v217
	s_lshl_b32 s24, s78, 6
	s_lshl_b32 s46, s76, 20
	v_and_b32_e32 v9, 63, v8
	v_or_b32_e32 v0, s24, v9
	v_ashrrev_i32_e32 v2, 6, v8
	v_lshlrev_b32_e32 v0, 2, v0
	v_lshl_add_u64 v[4:5], s[22:23], 0, v[0:1]
	v_ashrrev_i32_e32 v3, 31, v2
	v_lshl_add_u64 v[4:5], v[4:5], 0, s[46:47]
	v_lshlrev_b64 v[6:7], 12, v[2:3]
	v_lshl_add_u64 v[4:5], v[4:5], 0, v[6:7]
	v_add_co_u32_e32 v6, vcc, s33, v4
	global_load_dword v0, v[4:5], off nt
	s_nop 0
	v_addc_co_u32_e32 v7, vcc, 0, v5, vcc
	global_load_dword v3, v[6:7], off nt
	v_add_co_u32_e32 v6, vcc, s54, v4
	s_mov_b32 s25, 0x28000
	s_nop 0
	v_addc_co_u32_e32 v7, vcc, 0, v5, vcc
	global_load_dword v10, v[6:7], off nt
	v_add_co_u32_e32 v6, vcc, s27, v4
	v_lshlrev_b32_e32 v2, 2, v2
	s_nop 0
	v_addc_co_u32_e32 v7, vcc, 0, v5, vcc
	global_load_dword v11, v[6:7], off nt
	v_add_co_u32_e32 v6, vcc, s38, v4
	v_readlane_b32 s46, v255, 15
	s_nop 0
	v_addc_co_u32_e32 v7, vcc, 0, v5, vcc
	global_load_dword v12, v[6:7], off nt
	v_add_co_u32_e32 v6, vcc, s25, v4
	s_mov_b32 s25, 0x38000
	s_nop 0
	v_addc_co_u32_e32 v7, vcc, 0, v5, vcc
	global_load_dword v13, v[6:7], off nt
	v_add_co_u32_e32 v6, vcc, s39, v4
	s_nop 1
	v_addc_co_u32_e32 v7, vcc, 0, v5, vcc
	global_load_dword v14, v[6:7], off nt
	v_add_co_u32_e32 v6, vcc, s25, v4
	s_mov_b32 s25, 0x40000
	s_nop 0
	v_addc_co_u32_e32 v7, vcc, 0, v5, vcc
	global_load_dword v15, v[6:7], off nt
	v_add_co_u32_e32 v6, vcc, s25, v4
	s_mov_b32 s25, 0x48000
	s_nop 0
	v_addc_co_u32_e32 v7, vcc, 0, v5, vcc
	global_load_dword v16, v[6:7], off nt
	v_add_co_u32_e32 v6, vcc, s25, v4
	s_mov_b32 s25, 0x50000
	s_nop 0
	v_addc_co_u32_e32 v7, vcc, 0, v5, vcc
	global_load_dword v17, v[6:7], off nt
	v_add_co_u32_e32 v6, vcc, s25, v4
	s_mov_b32 s25, 0x58000
	s_nop 0
	v_addc_co_u32_e32 v7, vcc, 0, v5, vcc
	global_load_dword v18, v[6:7], off nt
	v_add_co_u32_e32 v6, vcc, s25, v4
	s_mov_b32 s25, 0x60000
	s_nop 0
	v_addc_co_u32_e32 v7, vcc, 0, v5, vcc
	global_load_dword v19, v[6:7], off nt
	v_add_co_u32_e32 v6, vcc, s25, v4
	s_mov_b32 s25, 0x68000
	s_nop 0
	v_addc_co_u32_e32 v7, vcc, 0, v5, vcc
	global_load_dword v20, v[6:7], off nt
	v_add_co_u32_e32 v6, vcc, s25, v4
	s_mov_b32 s25, 0x70000
	s_nop 0
	v_addc_co_u32_e32 v7, vcc, 0, v5, vcc
	global_load_dword v21, v[6:7], off nt
	v_add_co_u32_e32 v6, vcc, s25, v4
	s_mov_b32 s25, 0x78000
	s_nop 0
; DEVI unsigned cvtpk(float lo, float hi) { unsigned r; asm volatile("v_cvt_pk_bf16_f32 %0, %1, %2" : "=v"(r) : "v"(lo), "v"(hi)); return r; }
; DEVI int ltid(int wv) { int t = (wv << 6) | (int)__builtin_amdgcn_mbcnt_hi(~0u, __builtin_amdgcn_mbcnt_lo(~0u, 0u)); asm volatile("" : "+v"(t)); return t; }
; template <int KT, class F> DEVI void cvt_tile(F colptr, int ldsrc, int k0, bf16_t* out, int ldo, int v0, float* tile, int wv) {
;     const int tid = ltid(wv);
;     constexpr int PITCH = KT * 64 + 1;
;     { const int vc = tid & 63, kk = tid >> 6; const float* cp = colptr(v0 + vc) + (size_t)k0 * ldsrc; float v[8 * KT];
; #pragma unroll
;       for (int r = 0; r < 8 * KT; ++r) v[r] = cp[(size_t)(r * 8 + kk) * ldsrc];
; #pragma unroll
;       for (int r = 0; r < 8 * KT; ++r) tile[vc * PITCH + r * 8 + kk] = v[r]; }
;     __syncthreads();
;     { const int vc = tid >> 3, k8 = (tid & 7) * 8;
; #pragma unroll
;       for (int q = 0; q < KT; ++q) { const float* tp = tile + vc * PITCH + q * 64 + k8;
;         u32x4 w = {cvtpk(tp[0], tp[1]), cvtpk(tp[2], tp[3]), cvtpk(tp[4], tp[5]), cvtpk(tp[6], tp[7])};
;         *(u32x4*)(out + (size_t)(v0 + vc) * ldo + k0 + q * 64 + k8) = w; } }
;     __syncthreads();
; }
; DEVI void cvt_mix_phase(const float* win, const float* woa, const float* wor, const float* wout, const float* lwa, const float* lwx, unsigned char* ws, char* lds, int wv) {
;     ...
;             else cvt_tile<4>(ColLin{src}, DM, kg * 256, (bf16_t*)(ws + WS_WOUT), DM, vt * 64, tile, wv); }
	v_addc_co_u32_e32 v7, vcc, 0, v5, vcc
	global_load_dword v22, v[6:7], off nt
	v_add_co_u32_e32 v6, vcc, s25, v4
	s_mov_b32 s25, 0x80000
	s_nop 0
	v_addc_co_u32_e32 v7, vcc, 0, v5, vcc
	global_load_dword v23, v[6:7], off nt
	v_add_co_u32_e32 v6, vcc, s25, v4
	s_mov_b32 s25, 0x88000
	s_nop 0
	v_addc_co_u32_e32 v7, vcc, 0, v5, vcc
	global_load_dword v24, v[6:7], off nt
	v_add_co_u32_e32 v6, vcc, s25, v4
	s_mov_b32 s25, 0x90000
	s_nop 0
	v_addc_co_u32_e32 v7, vcc, 0, v5, vcc
	global_load_dword v25, v[6:7], off nt
	v_add_co_u32_e32 v6, vcc, s25, v4
	s_mov_b32 s25, 0x98000
	s_nop 0
	v_addc_co_u32_e32 v7, vcc, 0, v5, vcc
	global_load_dword v26, v[6:7], off nt
	v_add_co_u32_e32 v6, vcc, s25, v4
	s_mov_b32 s25, 0xa0000
	s_nop 0
	v_addc_co_u32_e32 v7, vcc, 0, v5, vcc
	global_load_dword v27, v[6:7], off nt
	v_add_co_u32_e32 v6, vcc, s25, v4
	s_mov_b32 s25, 0xa8000
	s_nop 0
	v_addc_co_u32_e32 v7, vcc, 0, v5, vcc
	global_load_dword v28, v[6:7], off nt
	v_add_co_u32_e32 v6, vcc, s25, v4
	s_mov_b32 s25, 0xb0000
	s_nop 0
	v_addc_co_u32_e32 v7, vcc, 0, v5, vcc
	global_load_dword v29, v[6:7], off nt
	v_add_co_u32_e32 v6, vcc, s25, v4
	s_mov_b32 s25, 0xb8000
	s_nop 0
	v_addc_co_u32_e32 v7, vcc, 0, v5, vcc
	global_load_dword v30, v[6:7], off nt
	v_add_co_u32_e32 v6, vcc, s25, v4
	s_mov_b32 s25, 0xc0000
	s_nop 0
	v_addc_co_u32_e32 v7, vcc, 0, v5, vcc
	global_load_dword v31, v[6:7], off nt
	v_add_co_u32_e32 v6, vcc, s25, v4
	s_mov_b32 s25, 0xc8000
	s_nop 0
	v_addc_co_u32_e32 v7, vcc, 0, v5, vcc
	global_load_dword v32, v[6:7], off nt
	v_add_co_u32_e32 v6, vcc, s25, v4
	s_mov_b32 s25, 0xd0000
	s_nop 0
	v_addc_co_u32_e32 v7, vcc, 0, v5, vcc
	global_load_dword v33, v[6:7], off nt
	v_add_co_u32_e32 v6, vcc, s25, v4
	s_mov_b32 s25, 0xd8000
	s_nop 0
	v_addc_co_u32_e32 v7, vcc, 0, v5, vcc
	global_load_dword v34, v[6:7], off nt
	v_add_co_u32_e32 v6, vcc, s25, v4
	s_mov_b32 s25, 0xe0000
	s_nop 0
	v_addc_co_u32_e32 v7, vcc, 0, v5, vcc
	global_load_dword v35, v[6:7], off nt
	v_add_co_u32_e32 v6, vcc, s25, v4
	s_mov_b32 s25, 0xe8000
	s_nop 0
	v_addc_co_u32_e32 v7, vcc, 0, v5, vcc
	global_load_dword v36, v[6:7], off nt
	v_add_co_u32_e32 v6, vcc, s25, v4
	s_mov_b32 s25, 0xf0000
	s_nop 0
	v_addc_co_u32_e32 v7, vcc, 0, v5, vcc
	global_load_dword v37, v[6:7], off nt
	v_add_co_u32_e32 v6, vcc, s25, v4
	s_mov_b32 s25, 0xf8000
	s_nop 0
	v_addc_co_u32_e32 v7, vcc, 0, v5, vcc
	v_add_co_u32_e32 v4, vcc, s25, v4
	global_load_dword v6, v[6:7], off nt
	s_nop 0
	v_addc_co_u32_e32 v5, vcc, 0, v5, vcc
	global_load_dword v4, v[4:5], off nt
	v_mul_u32_u24_e32 v5, 0x404, v9
	v_add3_u32 v2, 0, v5, v2
	v_add_u32_e32 v2, 0x8000, v2
	s_waitcnt vmcnt(0)
	ds_write2_b32 v2, v0, v3 offset1:8
	ds_write2_b32 v2, v10, v11 offset0:16 offset1:24
	ds_write2_b32 v2, v12, v13 offset0:32 offset1:40
	ds_write2_b32 v2, v14, v15 offset0:48 offset1:56
	ds_write2_b32 v2, v16, v17 offset0:64 offset1:72
	ds_write2_b32 v2, v18, v19 offset0:80 offset1:88
	ds_write2_b32 v2, v20, v21 offset0:96 offset1:104
	ds_write2_b32 v2, v22, v23 offset0:112 offset1:120
	ds_write2_b32 v2, v24, v25 offset0:128 offset1:136
	ds_write2_b32 v2, v26, v27 offset0:144 offset1:152
	ds_write2_b32 v2, v28, v29 offset0:160 offset1:168
	ds_write2_b32 v2, v30, v31 offset0:176 offset1:184
	ds_write2_b32 v2, v32, v33 offset0:192 offset1:200
	ds_write2_b32 v2, v34, v35 offset0:208 offset1:216
	ds_write2_b32 v2, v36, v37 offset0:224 offset1:232
	ds_write2_b32 v2, v6, v4 offset0:240 offset1:248
	v_lshlrev_b32_e32 v2, 3, v8
	v_ashrrev_i32_e32 v0, 3, v8
	v_and_b32_e32 v4, 56, v2
	v_mul_lo_u32 v2, v0, s43
	v_lshlrev_b32_e32 v3, 2, v4
	v_add3_u32 v10, 0, v2, v3
	s_lshl_b32 s25, s76, 9
	v_add_u32_e32 v2, s24, v0
	s_add_u32 s82, s46, s25
	v_readlane_b32 s25, v255, 16
	v_ashrrev_i32_e32 v3, 31, v2
	s_addc_u32 s83, s25, 0
	v_lshlrev_b64 v[2:3], 11, v[2:3]
	v_add_u32_e32 v5, 0x8000, v10
	v_lshl_add_u64 v[2:3], s[82:83], 0, v[2:3]
	v_lshlrev_b32_e32 v0, 1, v4
	s_waitcnt lgkmcnt(0)
	s_barrier
	v_lshl_add_u64 v[6:7], v[2:3], 0, v[0:1]
	ds_read2_b32 v[2:3], v5 offset1:1
	v_add_u32_e32 v0, 0x8008, v10
	s_waitcnt lgkmcnt(0)
	v_cvt_pk_bf16_f32 v2, v2, v3
	ds_read2_b32 v[4:5], v0 offset1:1
	v_add_u32_e32 v0, 0x8010, v10
	s_waitcnt lgkmcnt(0)
	v_cvt_pk_bf16_f32 v3, v4, v5
	ds_read2_b32 v[4:5], v0 offset1:1
	v_add_u32_e32 v0, 0x8018, v10
	s_waitcnt lgkmcnt(0)
	v_cvt_pk_bf16_f32 v4, v4, v5
	ds_read2_b32 v[8:9], v0 offset1:1
	s_waitcnt lgkmcnt(0)
	v_cvt_pk_bf16_f32 v5, v8, v9
	flat_store_dwordx4 v[6:7], v[2:5]
	v_add_u32_e32 v0, 0x8100, v10
	ds_read2_b32 v[2:3], v0 offset1:1
	v_add_u32_e32 v0, 0x8108, v10
	s_waitcnt lgkmcnt(0)
	v_cvt_pk_bf16_f32 v2, v2, v3
	ds_read2_b32 v[4:5], v0 offset1:1
	v_add_u32_e32 v0, 0x8110, v10
	s_waitcnt lgkmcnt(0)
	v_cvt_pk_bf16_f32 v3, v4, v5
	ds_read2_b32 v[4:5], v0 offset1:1
	v_add_u32_e32 v0, 0x8118, v10
	s_waitcnt lgkmcnt(0)
	v_cvt_pk_bf16_f32 v4, v4, v5
	ds_read2_b32 v[8:9], v0 offset1:1
	s_waitcnt lgkmcnt(0)
	v_cvt_pk_bf16_f32 v5, v8, v9
	flat_store_dwordx4 v[6:7], v[2:5] offset:128
	v_add_u32_e32 v0, 0x8200, v10
	ds_read2_b32 v[2:3], v0 offset1:1
	v_add_u32_e32 v0, 0x8208, v10
	s_waitcnt lgkmcnt(0)
	v_cvt_pk_bf16_f32 v2, v2, v3
	ds_read2_b32 v[4:5], v0 offset1:1
	v_add_u32_e32 v0, 0x8210, v10
	s_waitcnt lgkmcnt(0)
	v_cvt_pk_bf16_f32 v3, v4, v5
	ds_read2_b32 v[4:5], v0 offset1:1
	v_add_u32_e32 v0, 0x8218, v10
	s_waitcnt lgkmcnt(0)
	v_cvt_pk_bf16_f32 v4, v4, v5
	ds_read2_b32 v[8:9], v0 offset1:1
	s_waitcnt lgkmcnt(0)
	v_cvt_pk_bf16_f32 v5, v8, v9
	flat_store_dwordx4 v[6:7], v[2:5] offset:256
	v_add_u32_e32 v0, 0x8300, v10
	ds_read2_b32 v[2:3], v0 offset1:1
	v_add_u32_e32 v0, 0x8308, v10
	s_waitcnt lgkmcnt(0)
	v_cvt_pk_bf16_f32 v2, v2, v3
	ds_read2_b32 v[4:5], v0 offset1:1
	v_add_u32_e32 v0, 0x8310, v10
	s_waitcnt lgkmcnt(0)
	v_cvt_pk_bf16_f32 v3, v4, v5
	ds_read2_b32 v[4:5], v0 offset1:1
	v_add_u32_e32 v0, 0x8318, v10
	s_waitcnt lgkmcnt(0)
	v_cvt_pk_bf16_f32 v4, v4, v5
	ds_read2_b32 v[8:9], v0 offset1:1
	s_waitcnt lgkmcnt(0)
	v_cvt_pk_bf16_f32 v5, v8, v9
	flat_store_dwordx4 v[6:7], v[2:5] offset:384
	s_waitcnt lgkmcnt(0)
	s_barrier
	s_mov_b64 s[24:25], 0
; DEVI unsigned cvtpk(float lo, float hi) { unsigned r; asm volatile("v_cvt_pk_bf16_f32 %0, %1, %2" : "=v"(r) : "v"(lo), "v"(hi)); return r; }
; DEVI int ltid(int wv) { int t = (wv << 6) | (int)__builtin_amdgcn_mbcnt_hi(~0u, __builtin_amdgcn_mbcnt_lo(~0u, 0u)); asm volatile("" : "+v"(t)); return t; }
; template <int KT, class F> DEVI void cvt_tile(F colptr, int ldsrc, int k0, bf16_t* out, int ldo, int v0, float* tile, int wv) {
;     const int tid = ltid(wv);
;     constexpr int PITCH = KT * 64 + 1;
;     { const int vc = tid & 63, kk = tid >> 6; const float* cp = colptr(v0 + vc) + (size_t)k0 * ldsrc; float v[8 * KT];
; #pragma unroll
;       for (int r = 0; r < 8 * KT; ++r) v[r] = cp[(size_t)(r * 8 + kk) * ldsrc];
; #pragma unroll
;       for (int r = 0; r < 8 * KT; ++r) tile[vc * PITCH + r * 8 + kk] = v[r]; }
;     __syncthreads();
;     { const int vc = tid >> 3, k8 = (tid & 7) * 8;
; #pragma unroll
;       for (int q = 0; q < KT; ++q) { const float* tp = tile + vc * PITCH + q * 64 + k8;
;         u32x4 w = {cvtpk(tp[0], tp[1]), cvtpk(tp[2], tp[3]), cvtpk(tp[4], tp[5]), cvtpk(tp[6], tp[7])};
;         *(u32x4*)(out + (size_t)(v0 + vc) * ldo + k0 + q * 64 + k8) = w; } }
;     __syncthreads();
; }
; DEVI void cvt_mix_phase(const float* win, const float* woa, const float* wor, const float* wout, const float* lwa, const float* lwx, unsigned char* ws, char* lds, int wv) {
;     ...
;         else if (job < 448 + 192) { const int j = job - 448, m = j >> 6, jj = j & 63, vt = jj >> 2, kg = jj & 3;
;             const float* src = m == 0 ? woa : (m == 1 ? wor : wout);
;             if (m < 2) cvt_tile<4>(ColLin{src}, DM, kg * 256, (bf16_t*)(ws + WS_WOA) + m * DM, 2 * DM, vt * 64, tile, wv);
.LBB0_457:
	s_andn2_b64 vcc, exec, s[24:25]
	s_cbranch_vccnz .LBB0_459
	s_cmp_lt_u32 s80, 64
	s_cselect_b32 s81, s61, s23
	s_cselect_b32 s80, s60, s22
	s_lshl_b32 s22, s79, 11
	v_readlane_b32 s23, v255, 21
	s_add_u32 s23, s23, s22
	v_readlane_b32 s22, v255, 22
	v_mov_b32_e32 v8, v217
	s_addc_u32 s24, s22, 0
	s_lshl_b32 s22, s78, 6
	s_lshl_b32 s46, s76, 20
	v_and_b32_e32 v9, 63, v8
	v_or_b32_e32 v0, s22, v9
	v_ashrrev_i32_e32 v2, 6, v8
	v_lshlrev_b32_e32 v0, 2, v0
	v_lshl_add_u64 v[4:5], s[80:81], 0, v[0:1]
	v_ashrrev_i32_e32 v3, 31, v2
	v_lshl_add_u64 v[4:5], v[4:5], 0, s[46:47]
	v_lshlrev_b64 v[6:7], 12, v[2:3]
	v_lshl_add_u64 v[4:5], v[4:5], 0, v[6:7]
	v_add_co_u32_e32 v6, vcc, s33, v4
	global_load_dword v0, v[4:5], off nt
	s_nop 0
	v_addc_co_u32_e32 v7, vcc, 0, v5, vcc
	global_load_dword v3, v[6:7], off nt
	v_add_co_u32_e32 v6, vcc, s54, v4
	s_mov_b32 s25, 0x28000
	s_nop 0
	v_addc_co_u32_e32 v7, vcc, 0, v5, vcc
	global_load_dword v10, v[6:7], off nt
	v_add_co_u32_e32 v6, vcc, s27, v4
	v_lshlrev_b32_e32 v2, 2, v2
	s_nop 0
	v_addc_co_u32_e32 v7, vcc, 0, v5, vcc
	global_load_dword v11, v[6:7], off nt
	v_add_co_u32_e32 v6, vcc, s38, v4
	s_nop 1
	v_addc_co_u32_e32 v7, vcc, 0, v5, vcc
	global_load_dword v12, v[6:7], off nt
	v_add_co_u32_e32 v6, vcc, s25, v4
	s_mov_b32 s25, 0x38000
	s_nop 0
	v_addc_co_u32_e32 v7, vcc, 0, v5, vcc
	global_load_dword v13, v[6:7], off nt
	v_add_co_u32_e32 v6, vcc, s39, v4
	s_nop 1
	v_addc_co_u32_e32 v7, vcc, 0, v5, vcc
	global_load_dword v14, v[6:7], off nt
	v_add_co_u32_e32 v6, vcc, s25, v4
	s_mov_b32 s25, 0x40000
	s_nop 0
	v_addc_co_u32_e32 v7, vcc, 0, v5, vcc
	global_load_dword v15, v[6:7], off nt
	v_add_co_u32_e32 v6, vcc, s25, v4
	s_mov_b32 s25, 0x48000
	s_nop 0
	v_addc_co_u32_e32 v7, vcc, 0, v5, vcc
	global_load_dword v16, v[6:7], off nt
	v_add_co_u32_e32 v6, vcc, s25, v4
	s_mov_b32 s25, 0x50000
	s_nop 0
	v_addc_co_u32_e32 v7, vcc, 0, v5, vcc
	global_load_dword v17, v[6:7], off nt
	v_add_co_u32_e32 v6, vcc, s25, v4
	s_mov_b32 s25, 0x58000
	s_nop 0
	v_addc_co_u32_e32 v7, vcc, 0, v5, vcc
	global_load_dword v18, v[6:7], off nt
	v_add_co_u32_e32 v6, vcc, s25, v4
	s_mov_b32 s25, 0x60000
	s_nop 0
	v_addc_co_u32_e32 v7, vcc, 0, v5, vcc
	global_load_dword v19, v[6:7], off nt
	v_add_co_u32_e32 v6, vcc, s25, v4
	s_mov_b32 s25, 0x68000
	s_nop 0
	v_addc_co_u32_e32 v7, vcc, 0, v5, vcc
	global_load_dword v20, v[6:7], off nt
	v_add_co_u32_e32 v6, vcc, s25, v4
	s_mov_b32 s25, 0x70000
	s_nop 0
	v_addc_co_u32_e32 v7, vcc, 0, v5, vcc
	global_load_dword v21, v[6:7], off nt
	v_add_co_u32_e32 v6, vcc, s25, v4
	s_mov_b32 s25, 0x78000
	s_nop 0
	v_addc_co_u32_e32 v7, vcc, 0, v5, vcc
	global_load_dword v22, v[6:7], off nt
	v_add_co_u32_e32 v6, vcc, s25, v4
	s_mov_b32 s25, 0x80000
	s_nop 0
	v_addc_co_u32_e32 v7, vcc, 0, v5, vcc
	global_load_dword v23, v[6:7], off nt
	v_add_co_u32_e32 v6, vcc, s25, v4
	s_mov_b32 s25, 0x88000
	s_nop 0
	v_addc_co_u32_e32 v7, vcc, 0, v5, vcc
	global_load_dword v24, v[6:7], off nt
	v_add_co_u32_e32 v6, vcc, s25, v4
	s_mov_b32 s25, 0x90000
	s_nop 0
	v_addc_co_u32_e32 v7, vcc, 0, v5, vcc
	global_load_dword v25, v[6:7], off nt
	v_add_co_u32_e32 v6, vcc, s25, v4
	s_mov_b32 s25, 0x98000
	s_nop 0
	v_addc_co_u32_e32 v7, vcc, 0, v5, vcc
	global_load_dword v26, v[6:7], off nt
	v_add_co_u32_e32 v6, vcc, s25, v4
	s_mov_b32 s25, 0xa0000
	s_nop 0
	v_addc_co_u32_e32 v7, vcc, 0, v5, vcc
	global_load_dword v27, v[6:7], off nt
	v_add_co_u32_e32 v6, vcc, s25, v4
	s_mov_b32 s25, 0xa8000
	s_nop 0
	v_addc_co_u32_e32 v7, vcc, 0, v5, vcc
	global_load_dword v28, v[6:7], off nt
	v_add_co_u32_e32 v6, vcc, s25, v4
	s_mov_b32 s25, 0xb0000
	s_nop 0
	v_addc_co_u32_e32 v7, vcc, 0, v5, vcc
	global_load_dword v29, v[6:7], off nt
	v_add_co_u32_e32 v6, vcc, s25, v4
	s_mov_b32 s25, 0xb8000
	s_nop 0
	v_addc_co_u32_e32 v7, vcc, 0, v5, vcc
	global_load_dword v30, v[6:7], off nt
	v_add_co_u32_e32 v6, vcc, s25, v4
	s_mov_b32 s25, 0xc0000
	s_nop 0
	v_addc_co_u32_e32 v7, vcc, 0, v5, vcc
	global_load_dword v31, v[6:7], off nt
	v_add_co_u32_e32 v6, vcc, s25, v4
	s_mov_b32 s25, 0xc8000
	s_nop 0
	v_addc_co_u32_e32 v7, vcc, 0, v5, vcc
	global_load_dword v32, v[6:7], off nt
	v_add_co_u32_e32 v6, vcc, s25, v4
	s_mov_b32 s25, 0xd0000
	s_nop 0
	v_addc_co_u32_e32 v7, vcc, 0, v5, vcc
	global_load_dword v33, v[6:7], off nt
	v_add_co_u32_e32 v6, vcc, s25, v4
	s_mov_b32 s25, 0xd8000
	s_nop 0
	v_addc_co_u32_e32 v7, vcc, 0, v5, vcc
	global_load_dword v34, v[6:7], off nt
	v_add_co_u32_e32 v6, vcc, s25, v4
	s_mov_b32 s25, 0xe0000
	s_nop 0
	v_addc_co_u32_e32 v7, vcc, 0, v5, vcc
	global_load_dword v35, v[6:7], off nt
	v_add_co_u32_e32 v6, vcc, s25, v4
	s_mov_b32 s25, 0xe8000
	s_nop 0
	v_addc_co_u32_e32 v7, vcc, 0, v5, vcc
	global_load_dword v36, v[6:7], off nt
	v_add_co_u32_e32 v6, vcc, s25, v4
	s_mov_b32 s25, 0xf0000
	s_nop 0
	v_addc_co_u32_e32 v7, vcc, 0, v5, vcc
	global_load_dword v37, v[6:7], off nt
	v_add_co_u32_e32 v6, vcc, s25, v4
	s_mov_b32 s25, 0xf8000
	s_nop 0
	v_addc_co_u32_e32 v7, vcc, 0, v5, vcc
	v_add_co_u32_e32 v4, vcc, s25, v4
	global_load_dword v6, v[6:7], off nt
	s_nop 0
	v_addc_co_u32_e32 v5, vcc, 0, v5, vcc
	global_load_dword v4, v[4:5], off nt
	v_mul_u32_u24_e32 v5, 0x404, v9
	v_add3_u32 v2, 0, v5, v2
	v_add_u32_e32 v2, 0x8000, v2
	s_waitcnt vmcnt(0)
	ds_write2_b32 v2, v0, v3 offset1:8
	ds_write2_b32 v2, v10, v11 offset0:16 offset1:24
	ds_write2_b32 v2, v12, v13 offset0:32 offset1:40
	ds_write2_b32 v2, v14, v15 offset0:48 offset1:56
	ds_write2_b32 v2, v16, v17 offset0:64 offset1:72
	ds_write2_b32 v2, v18, v19 offset0:80 offset1:88
	ds_write2_b32 v2, v20, v21 offset0:96 offset1:104
	ds_write2_b32 v2, v22, v23 offset0:112 offset1:120
	ds_write2_b32 v2, v24, v25 offset0:128 offset1:136
	ds_write2_b32 v2, v26, v27 offset0:144 offset1:152
	ds_write2_b32 v2, v28, v29 offset0:160 offset1:168
	ds_write2_b32 v2, v30, v31 offset0:176 offset1:184
	ds_write2_b32 v2, v32, v33 offset0:192 offset1:200
	ds_write2_b32 v2, v34, v35 offset0:208 offset1:216
	ds_write2_b32 v2, v36, v37 offset0:224 offset1:232
	ds_write2_b32 v2, v6, v4 offset0:240 offset1:248
	v_lshlrev_b32_e32 v2, 3, v8
	v_ashrrev_i32_e32 v0, 3, v8
	v_and_b32_e32 v4, 56, v2
	v_mul_lo_u32 v2, v0, s43
	v_lshlrev_b32_e32 v3, 2, v4
	v_add3_u32 v10, 0, v2, v3
	s_lshl_b32 s25, s76, 9
	v_add_u32_e32 v2, s22, v0
	s_add_u32 s78, s23, s25
	v_ashrrev_i32_e32 v3, 31, v2
	s_addc_u32 s79, s24, 0
	v_lshlrev_b64 v[2:3], 12, v[2:3]
	v_add_u32_e32 v5, 0x8000, v10
	v_lshl_add_u64 v[2:3], s[78:79], 0, v[2:3]
	v_lshlrev_b32_e32 v0, 1, v4
	s_waitcnt lgkmcnt(0)
	s_barrier
; DEVI unsigned cvtpk(float lo, float hi) { unsigned r; asm volatile("v_cvt_pk_bf16_f32 %0, %1, %2" : "=v"(r) : "v"(lo), "v"(hi)); return r; }
; template <int KT, class F> DEVI void cvt_tile(F colptr, int ldsrc, int k0, bf16_t* out, int ldo, int v0, float* tile, int wv) {
;     ...
;     { const int vc = tid >> 3, k8 = (tid & 7) * 8;
; #pragma unroll
;       for (int q = 0; q < KT; ++q) { const float* tp = tile + vc * PITCH + q * 64 + k8;
;         u32x4 w = {cvtpk(tp[0], tp[1]), cvtpk(tp[2], tp[3]), cvtpk(tp[4], tp[5]), cvtpk(tp[6], tp[7])};
;         *(u32x4*)(out + (size_t)(v0 + vc) * ldo + k0 + q * 64 + k8) = w; } }
;     __syncthreads();
	v_lshl_add_u64 v[6:7], v[2:3], 0, v[0:1]
	ds_read2_b32 v[2:3], v5 offset1:1
	v_add_u32_e32 v0, 0x8008, v10
	s_waitcnt lgkmcnt(0)
	v_cvt_pk_bf16_f32 v2, v2, v3
	ds_read2_b32 v[4:5], v0 offset1:1
	v_add_u32_e32 v0, 0x8010, v10
	s_waitcnt lgkmcnt(0)
	v_cvt_pk_bf16_f32 v3, v4, v5
	ds_read2_b32 v[4:5], v0 offset1:1
	v_add_u32_e32 v0, 0x8018, v10
	s_waitcnt lgkmcnt(0)
	v_cvt_pk_bf16_f32 v4, v4, v5
	ds_read2_b32 v[8:9], v0 offset1:1
	s_waitcnt lgkmcnt(0)
	v_cvt_pk_bf16_f32 v5, v8, v9
	flat_store_dwordx4 v[6:7], v[2:5]
	v_add_u32_e32 v0, 0x8100, v10
	ds_read2_b32 v[2:3], v0 offset1:1
	v_add_u32_e32 v0, 0x8108, v10
	s_waitcnt lgkmcnt(0)
	v_cvt_pk_bf16_f32 v2, v2, v3
	ds_read2_b32 v[4:5], v0 offset1:1
	v_add_u32_e32 v0, 0x8110, v10
	s_waitcnt lgkmcnt(0)
	v_cvt_pk_bf16_f32 v3, v4, v5
	ds_read2_b32 v[4:5], v0 offset1:1
	v_add_u32_e32 v0, 0x8118, v10
	s_waitcnt lgkmcnt(0)
	v_cvt_pk_bf16_f32 v4, v4, v5
	ds_read2_b32 v[8:9], v0 offset1:1
	s_waitcnt lgkmcnt(0)
	v_cvt_pk_bf16_f32 v5, v8, v9
	flat_store_dwordx4 v[6:7], v[2:5] offset:128
	v_add_u32_e32 v0, 0x8200, v10
	ds_read2_b32 v[2:3], v0 offset1:1
	v_add_u32_e32 v0, 0x8208, v10
	s_waitcnt lgkmcnt(0)
	v_cvt_pk_bf16_f32 v2, v2, v3
	ds_read2_b32 v[4:5], v0 offset1:1
	v_add_u32_e32 v0, 0x8210, v10
	s_waitcnt lgkmcnt(0)
	v_cvt_pk_bf16_f32 v3, v4, v5
	ds_read2_b32 v[4:5], v0 offset1:1
	v_add_u32_e32 v0, 0x8218, v10
	s_waitcnt lgkmcnt(0)
	v_cvt_pk_bf16_f32 v4, v4, v5
	ds_read2_b32 v[8:9], v0 offset1:1
	s_waitcnt lgkmcnt(0)
	v_cvt_pk_bf16_f32 v5, v8, v9
	flat_store_dwordx4 v[6:7], v[2:5] offset:256
	v_add_u32_e32 v0, 0x8300, v10
	ds_read2_b32 v[2:3], v0 offset1:1
	v_add_u32_e32 v0, 0x8308, v10
	s_waitcnt lgkmcnt(0)
	v_cvt_pk_bf16_f32 v2, v2, v3
	ds_read2_b32 v[4:5], v0 offset1:1
	v_add_u32_e32 v0, 0x8310, v10
	s_waitcnt lgkmcnt(0)
	v_cvt_pk_bf16_f32 v3, v4, v5
	ds_read2_b32 v[4:5], v0 offset1:1
	v_add_u32_e32 v0, 0x8318, v10
	s_waitcnt lgkmcnt(0)
	v_cvt_pk_bf16_f32 v4, v4, v5
	ds_read2_b32 v[8:9], v0 offset1:1
	s_waitcnt lgkmcnt(0)
	v_cvt_pk_bf16_f32 v5, v8, v9
	flat_store_dwordx4 v[6:7], v[2:5] offset:384
	s_waitcnt lgkmcnt(0)
	s_barrier

; DEVI unsigned cvtpk(float lo, float hi) { unsigned r; asm volatile("v_cvt_pk_bf16_f32 %0, %1, %2" : "=v"(r) : "v"(lo), "v"(hi)); return r; }
; DEVI int lbid() { int t = blockIdx.x; asm volatile("" : "+s"(t)); return t; }
; DEVI float wave_sum(float v) { v += dpp<0xB1>(v); v += dpp<0x4E>(v); v += dpp<0x124>(v); v += dpp<0x128>(v); return xrow16_sum(v); }
; DEVI void norm_phase(const float* __restrict__ x, const float* __restrict__ gain, bf16_t* __restrict__ out,
;                      const float* wf_src, const float* bf_src, float* logf, char* lds, int wv) {
;     ...
;     for (int row0 = lbid() * 8 + wave; row0 < T_TOK; row0 += 2 * nw) {
;         f32x4 v[2][4]; float ss[2];
; #pragma unroll
;         for (int q = 0; q < 2; ++q) { const int row = row0 + q * nw < T_TOK ? row0 + q * nw : row0; const float* xr = x + (size_t)row * DM;
; #pragma unroll
;             for (int j = 0; j < 4; ++j) v[q][j] = *(const f32x4*)(xr + j * 256 + lane * 4); }
; #pragma unroll
;         for (int q = 0; q < 2; ++q) { float s_ = 0.f;
; #pragma unroll
;             for (int j = 0; j < 4; ++j) s_ += v[q][j][0] * v[q][j][0] + v[q][j][1] * v[q][j][1] + v[q][j][2] * v[q][j][2] + v[q][j][3] * v[q][j][3];
;             ss[q] = wave_sum(s_); }
; #pragma unroll
;         for (int q = 0; q < 2; ++q) { const int row = row0 + q * nw; if (row >= T_TOK) break;
;             const float rstd = __builtin_amdgcn_rsqf(ss[q] * (1.f / 1024.f) + 1e-6f);
; #pragma unroll
;             for (int j = 0; j < 4; ++j) { v[q][j] = v[q][j] * rstd * g[j]; u32x2 w; w.x = cvtpk(v[q][j][0], v[q][j][1]); w.y = cvtpk(v[q][j][2], v[q][j][3]); *(u32x2*)(out + (size_t)row * DM + j * 256 + lane * 4) = w; }
.LBB0_479:
	v_ashrrev_i32_e32 v47, 31, v46
	v_lshlrev_b64 v[18:19], 12, v[46:47]
	v_lshl_add_u64 v[18:19], v[36:37], 0, v[18:19]
	flat_load_dwordx4 v[48:51], v[18:19]
	flat_load_dwordx4 v[52:55], v[18:19] offset:1024
	flat_load_dwordx4 v[64:67], v[18:19] offset:2048
	flat_load_dwordx4 v[68:71], v[18:19] offset:3072
	v_add_u32_e32 v44, s46, v46
	v_cmp_gt_i32_e64 s[22:23], s33, v44
	s_andn2_b64 vcc, exec, s[78:79]
	s_waitcnt vmcnt(0) lgkmcnt(0)
	v_mul_f32_e32 v0, v49, v49
	v_cndmask_b32_e64 v18, v46, v44, s[22:23]
	v_ashrrev_i32_e32 v19, 31, v18
	v_lshlrev_b64 v[18:19], 12, v[18:19]
	v_lshl_add_u64 v[18:19], v[36:37], 0, v[18:19]
	flat_load_dwordx4 v[30:33], v[18:19]
	flat_load_dwordx4 v[26:29], v[18:19] offset:1024
	flat_load_dwordx4 v[22:25], v[18:19] offset:2048
	s_nop 0
	flat_load_dwordx4 v[18:21], v[18:19] offset:3072
	v_mul_f32_e32 v35, v53, v53
	v_fmac_f32_e32 v0, v48, v48
	v_fmac_f32_e32 v35, v52, v52
	v_fmac_f32_e32 v0, v50, v50
	v_fmac_f32_e32 v35, v54, v54
	v_fmac_f32_e32 v0, v51, v51
	v_fmac_f32_e32 v35, v55, v55
	v_add_f32_e32 v0, v0, v35
	v_mul_f32_e32 v35, v65, v65
	v_fmac_f32_e32 v35, v64, v64
	v_fmac_f32_e32 v35, v66, v66
	v_fmac_f32_e32 v35, v67, v67
	v_add_f32_e32 v0, v0, v35
	v_mul_f32_e32 v35, v69, v69
	v_fmac_f32_e32 v35, v68, v68
	v_fmac_f32_e32 v35, v70, v70
	v_fmac_f32_e32 v35, v71, v71
	v_add_f32_e32 v0, v0, v35
	s_waitcnt vmcnt(0) lgkmcnt(0)
	v_mul_f32_e32 v45, v27, v27
	v_add_f32_dpp v0, v0, v0 quad_perm:[1,0,3,2] row_mask:0xf bank_mask:0xf bound_ctrl:1
	v_fmac_f32_e32 v45, v26, v26
	v_fmac_f32_e32 v45, v28, v28
	v_add_f32_dpp v0, v0, v0 quad_perm:[2,3,0,1] row_mask:0xf bank_mask:0xf bound_ctrl:1
	v_fmac_f32_e32 v45, v29, v29
	s_nop 0
	v_add_f32_dpp v0, v0, v0 row_ror:4 row_mask:0xf bank_mask:0xf bound_ctrl:1
	s_nop 1
	v_add_f32_dpp v0, v0, v0 row_ror:8 row_mask:0xf bank_mask:0xf bound_ctrl:1
	v_mov_b32_e32 v35, v0
	s_nop 1
	v_permlane16_swap_b32_e32 v0, v35
	v_add_f32_e32 v0, v0, v35
	v_mul_f32_e32 v35, v31, v31
	v_fmac_f32_e32 v35, v30, v30
	v_fmac_f32_e32 v35, v32, v32
	v_fmac_f32_e32 v35, v33, v33
	v_add_f32_e32 v35, v35, v45
	v_mul_f32_e32 v45, v23, v23
	v_fmac_f32_e32 v45, v22, v22
	v_mov_b32_e32 v56, v0
	v_fmac_f32_e32 v45, v24, v24
	s_nop 0
	v_permlane32_swap_b32_e32 v0, v56
	v_fmac_f32_e32 v45, v25, v25
	v_add_f32_e32 v35, v35, v45
	v_mul_f32_e32 v45, v19, v19
	v_add_f32_e32 v0, v0, v56
	v_fmac_f32_e32 v45, v18, v18
	v_fmamk_f32 v0, v0, 0x3a800000, v216
	v_fmac_f32_e32 v45, v20, v20
	v_rsq_f32_e32 v0, v0
	v_fmac_f32_e32 v45, v21, v21
	v_add_f32_e32 v35, v35, v45
	v_lshlrev_b64 v[56:57], 11, v[46:47]
	v_pk_mul_f32 v[48:49], v[48:49], v[0:1] op_sel_hi:[1,0]
	v_add_f32_dpp v35, v35, v35 quad_perm:[1,0,3,2] row_mask:0xf bank_mask:0xf bound_ctrl:1
	v_pk_mul_f32 v[50:51], v[50:51], v[0:1] op_sel_hi:[1,0]
	v_lshl_add_u64 v[72:73], v[38:39], 0, v[56:57]
	v_add_f32_dpp v35, v35, v35 quad_perm:[2,3,0,1] row_mask:0xf bank_mask:0xf bound_ctrl:1
	v_pk_mul_f32 v[60:61], v[4:5], v[50:51]
	v_pk_mul_f32 v[62:63], v[2:3], v[48:49]
	v_add_f32_dpp v35, v35, v35 row_ror:4 row_mask:0xf bank_mask:0xf bound_ctrl:1
	v_cvt_pk_bf16_f32 v48, v62, v63
	v_cvt_pk_bf16_f32 v49, v60, v61
	flat_store_dwordx2 v[72:73], v[48:49]
	v_pk_mul_f32 v[48:49], v[52:53], v[0:1] op_sel_hi:[1,0]
	v_add_f32_dpp v35, v35, v35 row_ror:8 row_mask:0xf bank_mask:0xf bound_ctrl:1
	v_pk_mul_f32 v[50:51], v[54:55], v[0:1] op_sel_hi:[1,0]
	v_mov_b32_e32 v45, v35
	v_pk_mul_f32 v[56:57], v[8:9], v[50:51]
	v_pk_mul_f32 v[58:59], v[6:7], v[48:49]
	v_permlane16_swap_b32_e32 v35, v45
	v_cvt_pk_bf16_f32 v48, v58, v59
	v_cvt_pk_bf16_f32 v49, v56, v57
	flat_store_dwordx2 v[72:73], v[48:49] offset:512
	v_pk_mul_f32 v[48:49], v[64:65], v[0:1] op_sel_hi:[1,0]
	v_pk_mul_f32 v[50:51], v[66:67], v[0:1] op_sel_hi:[1,0]
	v_add_f32_e32 v35, v35, v45
	v_pk_mul_f32 v[52:53], v[12:13], v[50:51]
	v_pk_mul_f32 v[54:55], v[10:11], v[48:49]
	v_mov_b32_e32 v45, v35
	v_cvt_pk_bf16_f32 v48, v54, v55
	v_cvt_pk_bf16_f32 v49, v52, v53
	flat_store_dwordx2 v[72:73], v[48:49] offset:1024
	v_pk_mul_f32 v[50:51], v[68:69], v[0:1] op_sel_hi:[1,0]
	v_pk_mul_f32 v[48:49], v[70:71], v[0:1] op_sel_hi:[1,0]
	v_cndmask_b32_e64 v0, 0, 1, s[78:79]
	v_permlane32_swap_b32_e32 v35, v45
	v_pk_mul_f32 v[48:49], v[16:17], v[48:49]
	v_pk_mul_f32 v[50:51], v[14:15], v[50:51]
	v_cmp_ne_u32_e64 s[24:25], 1, v0
	v_cvt_pk_bf16_f32 v64, v50, v51
	v_cvt_pk_bf16_f32 v65, v48, v49
	flat_store_dwordx2 v[72:73], v[64:65] offset:1536
	s_cbranch_vccnz .LBB0_483
; DEVI float wave_sum(float v) { v += dpp<0xB1>(v); v += dpp<0x4E>(v); v += dpp<0x124>(v); v += dpp<0x128>(v); return xrow16_sum(v); }
; DEVI void norm_phase(const float* __restrict__ x, const float* __restrict__ gain, bf16_t* __restrict__ out,
;                      const float* wf_src, const float* bf_src, float* logf, char* lds, int wv) {
;     ...
;             if (wf_src) {
;                 float z = 0.f;
; #pragma unroll
;                 for (int h = 0; h < 8; ++h) { float d = 0.f;
; #pragma unroll
;                     for (int j = 0; j < 4; ++j) { const f32x4 w = *(const f32x4*)(wf + h * 1024 + j * 256 + lane * 4); d += v[q][j][0] * w[0] + v[q][j][1] * w[1] + v[q][j][2] * w[2] + v[q][j][3] * w[3]; }
;                     d = wave_sum(d); if (lane == h) z = d; }
	v_add_u32_e32 v0, 0, v34
	ds_read_b128 v[64:67], v0
	s_waitcnt lgkmcnt(0)
	v_mul_f32_e32 v47, v63, v65
	v_fmac_f32_e32 v47, v62, v64
	v_fmac_f32_e32 v47, v60, v66
	v_fmac_f32_e32 v47, v61, v67
	ds_read_b128 v[64:67], v0 offset:1024
	v_add_f32_e32 v47, 0, v47
	s_waitcnt lgkmcnt(0)
	v_mul_f32_e32 v65, v59, v65
	v_fmac_f32_e32 v65, v58, v64
	v_fmac_f32_e32 v65, v56, v66
	v_fmac_f32_e32 v65, v57, v67
	v_add_f32_e32 v47, v47, v65
	ds_read_b128 v[64:67], v0 offset:2048
	s_waitcnt lgkmcnt(0)
	v_mul_f32_e32 v65, v55, v65
	v_fmac_f32_e32 v65, v54, v64
	v_fmac_f32_e32 v65, v52, v66
	v_fmac_f32_e32 v65, v53, v67
	v_add_f32_e32 v47, v47, v65
	ds_read_b128 v[64:67], v0 offset:3072
	s_waitcnt lgkmcnt(0)
	v_mul_f32_e32 v65, v51, v65
	v_fmac_f32_e32 v65, v50, v64
	v_fmac_f32_e32 v65, v48, v66
	v_fmac_f32_e32 v65, v49, v67
	ds_read_b128 v[66:69], v0 offset:4096
	v_add_f32_e32 v47, v47, v65
	s_waitcnt lgkmcnt(0)
	v_mul_f32_e32 v65, v63, v67
	v_fmac_f32_e32 v65, v62, v66
	v_fmac_f32_e32 v65, v60, v68
	v_fmac_f32_e32 v65, v61, v69
	ds_read_b128 v[66:69], v0 offset:5120
	v_add_f32_e32 v65, 0, v65
	v_add_f32_dpp v47, v47, v47 quad_perm:[1,0,3,2] row_mask:0xf bank_mask:0xf bound_ctrl:1
	s_waitcnt lgkmcnt(0)
	v_mul_f32_e32 v67, v59, v67
	v_fmac_f32_e32 v67, v58, v66
	v_fmac_f32_e32 v67, v56, v68
	v_fmac_f32_e32 v67, v57, v69
	v_add_f32_e32 v65, v65, v67
	ds_read_b128 v[66:69], v0 offset:6144
	v_add_f32_dpp v47, v47, v47 quad_perm:[2,3,0,1] row_mask:0xf bank_mask:0xf bound_ctrl:1
	s_waitcnt lgkmcnt(0)
	v_mul_f32_e32 v67, v55, v67
	v_fmac_f32_e32 v67, v54, v66
	v_fmac_f32_e32 v67, v52, v68
	v_fmac_f32_e32 v67, v53, v69
	v_add_f32_e32 v65, v65, v67
	ds_read_b128 v[66:69], v0 offset:7168
	v_add_f32_dpp v47, v47, v47 row_ror:4 row_mask:0xf bank_mask:0xf bound_ctrl:1
	s_waitcnt lgkmcnt(0)
	v_mul_f32_e32 v67, v51, v67
	v_fmac_f32_e32 v67, v50, v66
	v_fmac_f32_e32 v67, v48, v68
	v_fmac_f32_e32 v67, v49, v69
	ds_read_b128 v[68:71], v0 offset:8192
	v_add_f32_e32 v65, v65, v67
	v_add_f32_dpp v47, v47, v47 row_ror:8 row_mask:0xf bank_mask:0xf bound_ctrl:1
	v_mov_b32_e32 v64, v47
	v_add_f32_dpp v65, v65, v65 quad_perm:[1,0,3,2] row_mask:0xf bank_mask:0xf bound_ctrl:1
	s_waitcnt lgkmcnt(0)
	v_mul_f32_e32 v67, v63, v69
	v_fmac_f32_e32 v67, v62, v68
	v_fmac_f32_e32 v67, v60, v70
	v_fmac_f32_e32 v67, v61, v71
	ds_read_b128 v[68:71], v0 offset:9216
	v_add_f32_e32 v67, 0, v67
	v_add_f32_dpp v65, v65, v65 quad_perm:[2,3,0,1] row_mask:0xf bank_mask:0xf bound_ctrl:1
	v_permlane16_swap_b32_e32 v47, v64
	s_waitcnt lgkmcnt(0)
	v_mul_f32_e32 v69, v59, v69
	v_fmac_f32_e32 v69, v58, v68
	v_fmac_f32_e32 v69, v56, v70
	v_fmac_f32_e32 v69, v57, v71
	v_add_f32_e32 v67, v67, v69
	ds_read_b128 v[68:71], v0 offset:10240
	v_add_f32_dpp v65, v65, v65 row_ror:4 row_mask:0xf bank_mask:0xf bound_ctrl:1
	v_add_f32_e32 v47, v47, v64
	v_mov_b32_e32 v64, v47
	v_add_f32_dpp v65, v65, v65 row_ror:8 row_mask:0xf bank_mask:0xf bound_ctrl:1
	s_waitcnt lgkmcnt(0)
	v_mul_f32_e32 v69, v55, v69
	v_fmac_f32_e32 v69, v54, v68
	v_fmac_f32_e32 v69, v52, v70
	v_fmac_f32_e32 v69, v53, v71
	v_add_f32_e32 v67, v67, v69
	ds_read_b128 v[68:71], v0 offset:11264
	v_mov_b32_e32 v66, v65
	s_nop 1
	v_permlane16_swap_b32_e32 v65, v66
	v_add_f32_e32 v65, v65, v66
	s_waitcnt lgkmcnt(0)
	v_mul_f32_e32 v69, v51, v69
	v_fmac_f32_e32 v69, v50, v68
	v_fmac_f32_e32 v69, v48, v70
	v_fmac_f32_e32 v69, v49, v71
	ds_read_b128 v[70:73], v0 offset:12288
	v_add_f32_e32 v67, v67, v69
	v_mov_b32_e32 v66, v65
	v_permlane32_swap_b32_e32 v47, v64
	s_waitcnt lgkmcnt(0)
	v_mul_f32_e32 v69, v63, v71
	v_fmac_f32_e32 v69, v62, v70
	v_fmac_f32_e32 v69, v60, v72
	v_fmac_f32_e32 v69, v61, v73
	ds_read_b128 v[70:73], v0 offset:13312
	v_add_f32_e32 v69, 0, v69
	v_add_f32_dpp v67, v67, v67 quad_perm:[1,0,3,2] row_mask:0xf bank_mask:0xf bound_ctrl:1
	v_permlane32_swap_b32_e32 v65, v66
	s_waitcnt lgkmcnt(0)
	v_mul_f32_e32 v71, v59, v71
	v_fmac_f32_e32 v71, v58, v70
	v_fmac_f32_e32 v71, v56, v72
	v_fmac_f32_e32 v71, v57, v73
	v_add_f32_e32 v69, v69, v71
	ds_read_b128 v[70:73], v0 offset:14336
	v_add_f32_dpp v67, v67, v67 quad_perm:[2,3,0,1] row_mask:0xf bank_mask:0xf bound_ctrl:1
	s_waitcnt lgkmcnt(0)
	v_mul_f32_e32 v71, v55, v71
	v_fmac_f32_e32 v71, v54, v70
	v_fmac_f32_e32 v71, v52, v72
	v_fmac_f32_e32 v71, v53, v73
	v_add_f32_e32 v69, v69, v71
	ds_read_b128 v[70:73], v0 offset:15360
	v_add_f32_dpp v67, v67, v67 row_ror:4 row_mask:0xf bank_mask:0xf bound_ctrl:1
	s_waitcnt lgkmcnt(0)
	v_mul_f32_e32 v71, v51, v71
	v_fmac_f32_e32 v71, v50, v70
	v_fmac_f32_e32 v71, v48, v72
	v_fmac_f32_e32 v71, v49, v73
	ds_read_b128 v[72:75], v0 offset:16384
	v_add_f32_e32 v69, v69, v71
	v_add_f32_dpp v67, v67, v67 row_ror:8 row_mask:0xf bank_mask:0xf bound_ctrl:1
	v_mov_b32_e32 v68, v67
	v_add_f32_dpp v69, v69, v69 quad_perm:[1,0,3,2] row_mask:0xf bank_mask:0xf bound_ctrl:1
	s_waitcnt lgkmcnt(0)
	v_mul_f32_e32 v71, v63, v73
	v_fmac_f32_e32 v71, v62, v72
	v_fmac_f32_e32 v71, v60, v74
	v_fmac_f32_e32 v71, v61, v75
	ds_read_b128 v[72:75], v0 offset:17408
	v_add_f32_e32 v71, 0, v71
	v_add_f32_dpp v69, v69, v69 quad_perm:[2,3,0,1] row_mask:0xf bank_mask:0xf bound_ctrl:1
	v_permlane16_swap_b32_e32 v67, v68
	s_waitcnt lgkmcnt(0)
	v_mul_f32_e32 v73, v59, v73
	v_fmac_f32_e32 v73, v58, v72
	v_fmac_f32_e32 v73, v56, v74
	v_fmac_f32_e32 v73, v57, v75
	v_add_f32_e32 v71, v71, v73
	ds_read_b128 v[72:75], v0 offset:18432
	v_add_f32_dpp v69, v69, v69 row_ror:4 row_mask:0xf bank_mask:0xf bound_ctrl:1
	v_add_f32_e32 v67, v67, v68
	v_mov_b32_e32 v68, v67
	v_add_f32_dpp v69, v69, v69 row_ror:8 row_mask:0xf bank_mask:0xf bound_ctrl:1
	s_waitcnt lgkmcnt(0)
; DEVI float wave_sum(float v) { v += dpp<0xB1>(v); v += dpp<0x4E>(v); v += dpp<0x124>(v); v += dpp<0x128>(v); return xrow16_sum(v); }
; DEVI void norm_phase(const float* __restrict__ x, const float* __restrict__ gain, bf16_t* __restrict__ out,
;                      const float* wf_src, const float* bf_src, float* logf, char* lds, int wv) {
;     ...
;                 for (int h = 0; h < 8; ++h) { float d = 0.f;
; #pragma unroll
;                     for (int j = 0; j < 4; ++j) { const f32x4 w = *(const f32x4*)(wf + h * 1024 + j * 256 + lane * 4); d += v[q][j][0] * w[0] + v[q][j][1] * w[1] + v[q][j][2] * w[2] + v[q][j][3] * w[3]; }
;                     d = wave_sum(d); if (lane == h) z = d; }
;                 if (lane < 8) { z += bf_src[lane]; logf[((size_t)(row >> 14) * 8 + lane) * SEQ + (row & (SEQ - 1))] = fminf(z, 0.f) - __logf(1.f + __expf(-fabsf(z))); }
	v_mul_f32_e32 v73, v55, v73
	v_fmac_f32_e32 v73, v54, v72
	v_fmac_f32_e32 v73, v52, v74
	v_fmac_f32_e32 v73, v53, v75
	v_add_f32_e32 v71, v71, v73
	ds_read_b128 v[72:75], v0 offset:19456
	v_mov_b32_e32 v70, v69
	s_nop 1
	v_permlane16_swap_b32_e32 v69, v70
	v_add_f32_e32 v69, v69, v70
	s_waitcnt lgkmcnt(0)
	v_mul_f32_e32 v73, v51, v73
	v_fmac_f32_e32 v73, v50, v72
	v_fmac_f32_e32 v73, v48, v74
	v_fmac_f32_e32 v73, v49, v75
	ds_read_b128 v[74:77], v0 offset:20480
	v_add_f32_e32 v71, v71, v73
	v_mov_b32_e32 v70, v69
	v_permlane32_swap_b32_e32 v67, v68
	s_waitcnt lgkmcnt(0)
	v_mul_f32_e32 v73, v63, v75
	v_fmac_f32_e32 v73, v62, v74
	v_fmac_f32_e32 v73, v60, v76
	v_fmac_f32_e32 v73, v61, v77
	ds_read_b128 v[74:77], v0 offset:21504
	v_add_f32_e32 v73, 0, v73
	v_add_f32_dpp v71, v71, v71 quad_perm:[1,0,3,2] row_mask:0xf bank_mask:0xf bound_ctrl:1
	v_permlane32_swap_b32_e32 v69, v70
	s_waitcnt lgkmcnt(0)
	v_mul_f32_e32 v75, v59, v75
	v_fmac_f32_e32 v75, v58, v74
	v_fmac_f32_e32 v75, v56, v76
	v_fmac_f32_e32 v75, v57, v77
	v_add_f32_e32 v73, v73, v75
	ds_read_b128 v[74:77], v0 offset:22528
	v_add_f32_dpp v71, v71, v71 quad_perm:[2,3,0,1] row_mask:0xf bank_mask:0xf bound_ctrl:1
	s_waitcnt lgkmcnt(0)
	v_mul_f32_e32 v75, v55, v75
	v_fmac_f32_e32 v75, v54, v74
	v_fmac_f32_e32 v75, v52, v76
	v_fmac_f32_e32 v75, v53, v77
	v_add_f32_e32 v73, v73, v75
	ds_read_b128 v[74:77], v0 offset:23552
	v_add_f32_dpp v71, v71, v71 row_ror:4 row_mask:0xf bank_mask:0xf bound_ctrl:1
	s_waitcnt lgkmcnt(0)
	v_mul_f32_e32 v75, v51, v75
	v_fmac_f32_e32 v75, v50, v74
	v_fmac_f32_e32 v75, v48, v76
	v_fmac_f32_e32 v75, v49, v77
	ds_read_b128 v[76:79], v0 offset:24576
	v_add_f32_e32 v73, v73, v75
	v_add_f32_dpp v71, v71, v71 row_ror:8 row_mask:0xf bank_mask:0xf bound_ctrl:1
	v_mov_b32_e32 v72, v71
	v_add_f32_dpp v73, v73, v73 quad_perm:[1,0,3,2] row_mask:0xf bank_mask:0xf bound_ctrl:1
	s_waitcnt lgkmcnt(0)
	v_mul_f32_e32 v75, v63, v77
	v_fmac_f32_e32 v75, v62, v76
	v_fmac_f32_e32 v75, v60, v78
	v_fmac_f32_e32 v75, v61, v79
	ds_read_b128 v[76:79], v0 offset:25600
	v_add_f32_e32 v75, 0, v75
	v_add_f32_dpp v73, v73, v73 quad_perm:[2,3,0,1] row_mask:0xf bank_mask:0xf bound_ctrl:1
	v_permlane16_swap_b32_e32 v71, v72
	s_waitcnt lgkmcnt(0)
	v_mul_f32_e32 v77, v59, v77
	v_fmac_f32_e32 v77, v58, v76
	v_fmac_f32_e32 v77, v56, v78
	v_fmac_f32_e32 v77, v57, v79
	v_add_f32_e32 v75, v75, v77
	ds_read_b128 v[76:79], v0 offset:26624
	v_add_f32_dpp v73, v73, v73 row_ror:4 row_mask:0xf bank_mask:0xf bound_ctrl:1
	v_add_f32_e32 v71, v71, v72
	v_mov_b32_e32 v72, v71
	v_add_f32_dpp v73, v73, v73 row_ror:8 row_mask:0xf bank_mask:0xf bound_ctrl:1
	s_waitcnt lgkmcnt(0)
	v_mul_f32_e32 v77, v55, v77
	v_fmac_f32_e32 v77, v54, v76
	v_fmac_f32_e32 v77, v52, v78
	v_fmac_f32_e32 v77, v53, v79
	v_add_f32_e32 v75, v75, v77
	ds_read_b128 v[76:79], v0 offset:27648
	v_mov_b32_e32 v74, v73
	s_nop 1
	v_permlane16_swap_b32_e32 v73, v74
	v_add_f32_e32 v73, v73, v74
	s_waitcnt lgkmcnt(0)
	v_mul_f32_e32 v77, v51, v77
	v_fmac_f32_e32 v77, v50, v76
	v_fmac_f32_e32 v77, v48, v78
	v_fmac_f32_e32 v77, v49, v79
	ds_read_b128 v[78:81], v0 offset:28672
	v_add_f32_e32 v75, v75, v77
	v_mov_b32_e32 v74, v73
	v_permlane32_swap_b32_e32 v71, v72
	s_waitcnt lgkmcnt(0)
	v_mul_f32_e32 v63, v63, v79
	v_fmac_f32_e32 v63, v62, v78
	v_fmac_f32_e32 v63, v60, v80
	v_fmac_f32_e32 v63, v61, v81
	v_add_f32_e32 v77, 0, v63
	ds_read_b128 v[60:63], v0 offset:29696
	v_add_f32_dpp v75, v75, v75 quad_perm:[1,0,3,2] row_mask:0xf bank_mask:0xf bound_ctrl:1
	v_permlane32_swap_b32_e32 v73, v74
	s_nop 0
	v_add_f32_dpp v75, v75, v75 quad_perm:[2,3,0,1] row_mask:0xf bank_mask:0xf bound_ctrl:1
	s_waitcnt lgkmcnt(0)
	v_mul_f32_e32 v59, v59, v61
	v_fmac_f32_e32 v59, v58, v60
	v_fmac_f32_e32 v59, v56, v62
	v_fmac_f32_e32 v59, v57, v63
	v_add_f32_e32 v60, v77, v59
	ds_read_b128 v[56:59], v0 offset:30720
	v_add_f32_dpp v75, v75, v75 row_ror:4 row_mask:0xf bank_mask:0xf bound_ctrl:1
	s_waitcnt lgkmcnt(0)
	v_mul_f32_e32 v55, v55, v57
	v_fmac_f32_e32 v55, v54, v56
	v_fmac_f32_e32 v55, v52, v58
	v_fmac_f32_e32 v55, v53, v59
	v_add_f32_e32 v56, v60, v55
	ds_read_b128 v[52:55], v0 offset:31744
	v_add_f32_dpp v75, v75, v75 row_ror:8 row_mask:0xf bank_mask:0xf bound_ctrl:1
	v_mov_b32_e32 v76, v75
	s_nop 1
	v_permlane16_swap_b32_e32 v75, v76
	s_waitcnt lgkmcnt(0)
	v_mul_f32_e32 v0, v51, v53
	v_fmac_f32_e32 v0, v50, v52
	v_fmac_f32_e32 v0, v48, v54
	v_fmac_f32_e32 v0, v49, v55
	v_add_f32_e32 v0, v56, v0
	v_add_f32_e32 v75, v75, v76
	v_mov_b32_e32 v76, v75
	v_add_f32_dpp v0, v0, v0 quad_perm:[1,0,3,2] row_mask:0xf bank_mask:0xf bound_ctrl:1
	s_nop 0
	v_permlane32_swap_b32_e32 v75, v76
	v_add_f32_dpp v0, v0, v0 quad_perm:[2,3,0,1] row_mask:0xf bank_mask:0xf bound_ctrl:1
	s_nop 1
	v_add_f32_dpp v0, v0, v0 row_ror:4 row_mask:0xf bank_mask:0xf bound_ctrl:1
	s_nop 1
	v_add_f32_dpp v0, v0, v0 row_ror:8 row_mask:0xf bank_mask:0xf bound_ctrl:1
	v_mov_b32_e32 v48, v0
	s_nop 1
	v_permlane16_swap_b32_e32 v0, v48
	v_add_f32_e32 v0, v0, v48
	v_mov_b32_e32 v48, v0
	s_nop 1
	v_permlane32_swap_b32_e32 v0, v48
	s_and_saveexec_b64 s[84:85], s[4:5]
	s_cbranch_execz .LBB0_482
	global_load_dword v49, v[40:41], off nt
	v_add_f32_e32 v47, v47, v64
	v_add_f32_e32 v55, v65, v66
	v_cndmask_b32_e64 v47, 0, v47, s[20:21]
	v_add_f32_e32 v54, v67, v68
	v_cndmask_b32_e64 v47, v47, v55, s[18:19]
	v_add_f32_e32 v53, v69, v70
	v_cndmask_b32_e64 v47, v47, v54, s[16:17]
	v_add_f32_e32 v52, v71, v72
	v_cndmask_b32_e64 v47, v47, v53, s[14:15]
	v_add_f32_e32 v51, v73, v74
	v_cndmask_b32_e64 v47, v47, v52, s[12:13]
	v_add_f32_e32 v50, v75, v76
	v_cndmask_b32_e64 v47, v47, v51, s[10:11]
	v_add_f32_e32 v0, v0, v48
	v_cndmask_b32_e64 v47, v47, v50, s[8:9]
	v_cndmask_b32_e64 v0, v47, v0, s[6:7]
	s_mov_b32 s59, 0xbfb8aa3b
	v_ashrrev_i32_e32 v48, 14, v46
	v_and_b32_e32 v46, 0x3fff, v46
	s_waitcnt vmcnt(0)
	v_add_f32_e32 v50, v0, v49
	v_mul_f32_e64 v0, |v50|, s59
	v_exp_f32_e32 v51, v0
	v_ashrrev_i32_e32 v49, 31, v48
	v_lshlrev_b32_e32 v0, 2, v46
	v_lshlrev_b64 v[46:47], 19, v[48:49]
	v_add_f32_e32 v48, 1.0, v51
	s_mov_b32 s59, 0x800000
	v_cmp_gt_f32_e32 vcc, s59, v48
	s_mov_b32 s59, 0x3f317217
	v_lshl_add_u64 v[46:47], v[42:43], 0, v[46:47]
	v_cndmask_b32_e64 v49, 0, 32, vcc
	v_ldexp_f32 v48, v48, v49
	v_log_f32_e32 v48, v48
	v_min_f32_e32 v49, 0, v50
	v_mov_b32_e32 v50, 0x41b17218
	v_cndmask_b32_e32 v50, 0, v50, vcc
	v_mul_f32_e32 v51, 0x3f317217, v48
	v_fma_f32 v51, v48, s59, -v51
	v_fmac_f32_e32 v51, 0x3377d1cf, v48
	s_mov_b32 s59, 0x7f800000
	v_fmac_f32_e32 v51, 0x3f317217, v48
	v_cmp_lt_f32_e64 vcc, |v48|, s59
	v_lshl_add_u64 v[46:47], v[46:47], 0, v[0:1]
	s_nop 0
	v_cndmask_b32_e32 v48, v48, v51, vcc
	v_sub_f32_e32 v48, v48, v50
	v_sub_f32_e32 v48, v49, v48
	flat_store_dword v[46:47], v48

; DEVI unsigned cvtpk(float lo, float hi) { unsigned r; asm volatile("v_cvt_pk_bf16_f32 %0, %1, %2" : "=v"(r) : "v"(lo), "v"(hi)); return r; }
; DEVI float wave_sum(float v) { v += dpp<0xB1>(v); v += dpp<0x4E>(v); v += dpp<0x124>(v); v += dpp<0x128>(v); return xrow16_sum(v); }
; DEVI void norm_phase(const float* __restrict__ x, const float* __restrict__ gain, bf16_t* __restrict__ out,
;                      const float* wf_src, const float* bf_src, float* logf, char* lds, int wv) {
;     ...
;         for (int q = 0; q < 2; ++q) { const int row = row0 + q * nw; if (row >= T_TOK) break;
;             const float rstd = __builtin_amdgcn_rsqf(ss[q] * (1.f / 1024.f) + 1e-6f);
; #pragma unroll
;             for (int j = 0; j < 4; ++j) { v[q][j] = v[q][j] * rstd * g[j]; u32x2 w; w.x = cvtpk(v[q][j][0], v[q][j][1]); w.y = cvtpk(v[q][j][2], v[q][j][3]); *(u32x2*)(out + (size_t)row * DM + j * 256 + lane * 4) = w; }
;             if (wf_src) {
;                 float z = 0.f;
; #pragma unroll
;                 for (int h = 0; h < 8; ++h) { float d = 0.f;
; #pragma unroll
;                     for (int j = 0; j < 4; ++j) { const f32x4 w = *(const f32x4*)(wf + h * 1024 + j * 256 + lane * 4); d += v[q][j][0] * w[0] + v[q][j][1] * w[1] + v[q][j][2] * w[2] + v[q][j][3] * w[3]; }
;                     d = wave_sum(d); if (lane == h) z = d; }
.LBB0_483:
	s_and_saveexec_b64 s[84:85], s[22:23]
	s_cbranch_execz .LBB0_478
	v_add_f32_e32 v0, v35, v45
	v_fmamk_f32 v0, v0, 0x3a800000, v216
	v_rsq_f32_e32 v0, v0
	v_ashrrev_i32_e32 v45, 31, v44
	v_lshlrev_b64 v[46:47], 11, v[44:45]
	v_lshl_add_u64 v[46:47], v[38:39], 0, v[46:47]
	v_pk_mul_f32 v[32:33], v[32:33], v[0:1] op_sel_hi:[1,0]
	v_pk_mul_f32 v[48:49], v[30:31], v[0:1] op_sel_hi:[1,0]
	v_pk_mul_f32 v[30:31], v[4:5], v[32:33]
	v_pk_mul_f32 v[32:33], v[2:3], v[48:49]
	v_pk_mul_f32 v[28:29], v[28:29], v[0:1] op_sel_hi:[1,0]
	v_cvt_pk_bf16_f32 v48, v32, v33
	v_cvt_pk_bf16_f32 v49, v30, v31
	flat_store_dwordx2 v[46:47], v[48:49]
	v_pk_mul_f32 v[48:49], v[26:27], v[0:1] op_sel_hi:[1,0]
	v_pk_mul_f32 v[26:27], v[8:9], v[28:29]
	v_pk_mul_f32 v[28:29], v[6:7], v[48:49]
	v_pk_mul_f32 v[24:25], v[24:25], v[0:1] op_sel_hi:[1,0]
	v_cvt_pk_bf16_f32 v48, v28, v29
	v_cvt_pk_bf16_f32 v49, v26, v27
	flat_store_dwordx2 v[46:47], v[48:49] offset:512
	v_pk_mul_f32 v[48:49], v[22:23], v[0:1] op_sel_hi:[1,0]
	v_pk_mul_f32 v[22:23], v[12:13], v[24:25]
	v_pk_mul_f32 v[24:25], v[10:11], v[48:49]
	v_pk_mul_f32 v[20:21], v[20:21], v[0:1] op_sel_hi:[1,0]
	v_cvt_pk_bf16_f32 v48, v24, v25
	v_cvt_pk_bf16_f32 v49, v22, v23
	flat_store_dwordx2 v[46:47], v[48:49] offset:1024
	v_pk_mul_f32 v[48:49], v[18:19], v[0:1] op_sel_hi:[1,0]
	v_pk_mul_f32 v[18:19], v[16:17], v[20:21]
	v_pk_mul_f32 v[20:21], v[14:15], v[48:49]
	s_and_b64 vcc, exec, s[24:25]
	v_cvt_pk_bf16_f32 v48, v20, v21
	v_cvt_pk_bf16_f32 v49, v18, v19
	flat_store_dwordx2 v[46:47], v[48:49] offset:1536
	s_cbranch_vccnz .LBB0_478
	v_add_u32_e32 v0, 0, v34
	ds_read_b128 v[46:49], v0
	s_waitcnt lgkmcnt(0)
	v_mul_f32_e32 v35, v33, v47
	v_fmac_f32_e32 v35, v32, v46
	v_fmac_f32_e32 v35, v30, v48
	v_fmac_f32_e32 v35, v31, v49
	ds_read_b128 v[46:49], v0 offset:1024
	v_add_f32_e32 v35, 0, v35
	s_waitcnt lgkmcnt(0)
	v_mul_f32_e32 v45, v29, v47
	v_fmac_f32_e32 v45, v28, v46
	v_fmac_f32_e32 v45, v26, v48
	v_fmac_f32_e32 v45, v27, v49
	ds_read_b128 v[46:49], v0 offset:2048
	v_add_f32_e32 v35, v35, v45
	s_waitcnt lgkmcnt(0)
	v_mul_f32_e32 v45, v25, v47
	v_fmac_f32_e32 v45, v24, v46
	v_fmac_f32_e32 v45, v22, v48
	v_fmac_f32_e32 v45, v23, v49
	ds_read_b128 v[46:49], v0 offset:3072
	v_add_f32_e32 v35, v35, v45
	s_waitcnt lgkmcnt(0)
	v_mul_f32_e32 v45, v21, v47
	v_fmac_f32_e32 v45, v20, v46
	v_fmac_f32_e32 v45, v18, v48
	v_fmac_f32_e32 v45, v19, v49
	ds_read_b128 v[46:49], v0 offset:4096
	v_add_f32_e32 v35, v35, v45
	s_waitcnt lgkmcnt(0)
	v_mul_f32_e32 v47, v33, v47
	v_fmac_f32_e32 v47, v32, v46
	v_fmac_f32_e32 v47, v30, v48
	v_fmac_f32_e32 v47, v31, v49
	v_add_f32_e32 v50, 0, v47
	ds_read_b128 v[46:49], v0 offset:5120
	v_add_f32_dpp v35, v35, v35 quad_perm:[1,0,3,2] row_mask:0xf bank_mask:0xf bound_ctrl:1
	s_waitcnt lgkmcnt(0)
	v_mul_f32_e32 v47, v29, v47
	v_fmac_f32_e32 v47, v28, v46
	v_fmac_f32_e32 v47, v26, v48
	v_fmac_f32_e32 v47, v27, v49
	v_add_f32_e32 v50, v50, v47
	ds_read_b128 v[46:49], v0 offset:6144
	v_add_f32_dpp v35, v35, v35 quad_perm:[2,3,0,1] row_mask:0xf bank_mask:0xf bound_ctrl:1
	s_waitcnt lgkmcnt(0)
	v_mul_f32_e32 v47, v25, v47
	v_fmac_f32_e32 v47, v24, v46
	v_fmac_f32_e32 v47, v22, v48
	v_fmac_f32_e32 v47, v23, v49
	v_add_f32_e32 v50, v50, v47
	ds_read_b128 v[46:49], v0 offset:7168
	v_add_f32_dpp v35, v35, v35 row_ror:4 row_mask:0xf bank_mask:0xf bound_ctrl:1
	s_waitcnt lgkmcnt(0)
	v_mul_f32_e32 v47, v21, v47
	v_fmac_f32_e32 v47, v20, v46
	v_fmac_f32_e32 v47, v18, v48
	v_fmac_f32_e32 v47, v19, v49
	v_add_f32_e32 v46, v50, v47
	ds_read_b128 v[48:51], v0 offset:8192
	v_add_f32_dpp v35, v35, v35 row_ror:8 row_mask:0xf bank_mask:0xf bound_ctrl:1
	v_add_f32_dpp v46, v46, v46 quad_perm:[1,0,3,2] row_mask:0xf bank_mask:0xf bound_ctrl:1
	v_mov_b32_e32 v45, v35
	s_nop 1
	v_permlane16_swap_b32_e32 v35, v45
	s_waitcnt lgkmcnt(0)
	v_mul_f32_e32 v49, v33, v49
	v_fmac_f32_e32 v49, v32, v48
	v_fmac_f32_e32 v49, v30, v50
	v_fmac_f32_e32 v49, v31, v51
	v_add_f32_e32 v52, 0, v49
	ds_read_b128 v[48:51], v0 offset:9216
	v_add_f32_dpp v46, v46, v46 quad_perm:[2,3,0,1] row_mask:0xf bank_mask:0xf bound_ctrl:1
	v_add_f32_e32 v35, v35, v45
	v_mov_b32_e32 v45, v35
	v_add_f32_dpp v46, v46, v46 row_ror:4 row_mask:0xf bank_mask:0xf bound_ctrl:1
	s_waitcnt lgkmcnt(0)
	v_mul_f32_e32 v49, v29, v49
	v_fmac_f32_e32 v49, v28, v48
	v_fmac_f32_e32 v49, v26, v50
	v_fmac_f32_e32 v49, v27, v51
	v_add_f32_e32 v52, v52, v49
	ds_read_b128 v[48:51], v0 offset:10240
	v_add_f32_dpp v46, v46, v46 row_ror:8 row_mask:0xf bank_mask:0xf bound_ctrl:1
	v_mov_b32_e32 v47, v46
	s_nop 1
	v_permlane16_swap_b32_e32 v46, v47
	s_waitcnt lgkmcnt(0)
	v_mul_f32_e32 v49, v25, v49
	v_fmac_f32_e32 v49, v24, v48
	v_fmac_f32_e32 v49, v22, v50
	v_fmac_f32_e32 v49, v23, v51
	v_add_f32_e32 v52, v52, v49
	ds_read_b128 v[48:51], v0 offset:11264
	v_add_f32_e32 v46, v46, v47
	v_mov_b32_e32 v47, v46
	v_permlane32_swap_b32_e32 v35, v45
	s_waitcnt lgkmcnt(0)
	v_mul_f32_e32 v49, v21, v49
	v_fmac_f32_e32 v49, v20, v48
	v_fmac_f32_e32 v49, v18, v50
	v_fmac_f32_e32 v49, v19, v51
	v_add_f32_e32 v48, v52, v49
	ds_read_b128 v[50:53], v0 offset:12288
	v_permlane32_swap_b32_e32 v46, v47
	v_add_f32_dpp v48, v48, v48 quad_perm:[1,0,3,2] row_mask:0xf bank_mask:0xf bound_ctrl:1
	s_waitcnt lgkmcnt(0)
	v_mul_f32_e32 v51, v33, v51
	v_fmac_f32_e32 v51, v32, v50
	v_fmac_f32_e32 v51, v30, v52
	v_fmac_f32_e32 v51, v31, v53
	v_add_f32_e32 v54, 0, v51
	ds_read_b128 v[50:53], v0 offset:13312
	v_add_f32_dpp v48, v48, v48 quad_perm:[2,3,0,1] row_mask:0xf bank_mask:0xf bound_ctrl:1
	s_waitcnt lgkmcnt(0)
; DEVI float wave_sum(float v) { v += dpp<0xB1>(v); v += dpp<0x4E>(v); v += dpp<0x124>(v); v += dpp<0x128>(v); return xrow16_sum(v); }
; DEVI void norm_phase(const float* __restrict__ x, const float* __restrict__ gain, bf16_t* __restrict__ out,
;                      const float* wf_src, const float* bf_src, float* logf, char* lds, int wv) {
;     ...
;                 for (int h = 0; h < 8; ++h) { float d = 0.f;
; #pragma unroll
;                     for (int j = 0; j < 4; ++j) { const f32x4 w = *(const f32x4*)(wf + h * 1024 + j * 256 + lane * 4); d += v[q][j][0] * w[0] + v[q][j][1] * w[1] + v[q][j][2] * w[2] + v[q][j][3] * w[3]; }
;                     d = wave_sum(d); if (lane == h) z = d; }
	v_mul_f32_e32 v51, v29, v51
	v_fmac_f32_e32 v51, v28, v50
	v_fmac_f32_e32 v51, v26, v52
	v_fmac_f32_e32 v51, v27, v53
	v_add_f32_e32 v54, v54, v51
	ds_read_b128 v[50:53], v0 offset:14336
	v_add_f32_dpp v48, v48, v48 row_ror:4 row_mask:0xf bank_mask:0xf bound_ctrl:1
	s_waitcnt lgkmcnt(0)
	v_mul_f32_e32 v51, v25, v51
	v_fmac_f32_e32 v51, v24, v50
	v_fmac_f32_e32 v51, v22, v52
	v_fmac_f32_e32 v51, v23, v53
	v_add_f32_e32 v54, v54, v51
	ds_read_b128 v[50:53], v0 offset:15360
	v_add_f32_dpp v48, v48, v48 row_ror:8 row_mask:0xf bank_mask:0xf bound_ctrl:1
	v_mov_b32_e32 v49, v48
	s_nop 1
	v_permlane16_swap_b32_e32 v48, v49
	s_waitcnt lgkmcnt(0)
	v_mul_f32_e32 v51, v21, v51
	v_fmac_f32_e32 v51, v20, v50
	v_fmac_f32_e32 v51, v18, v52
	v_fmac_f32_e32 v51, v19, v53
	v_add_f32_e32 v50, v54, v51
	ds_read_b128 v[52:55], v0 offset:16384
	v_add_f32_e32 v48, v48, v49
	v_add_f32_dpp v50, v50, v50 quad_perm:[1,0,3,2] row_mask:0xf bank_mask:0xf bound_ctrl:1
	v_mov_b32_e32 v49, v48
	s_nop 1
	v_permlane32_swap_b32_e32 v48, v49
	s_waitcnt lgkmcnt(0)
	v_mul_f32_e32 v53, v33, v53
	v_fmac_f32_e32 v53, v32, v52
	v_fmac_f32_e32 v53, v30, v54
	v_fmac_f32_e32 v53, v31, v55
	v_add_f32_e32 v56, 0, v53
	ds_read_b128 v[52:55], v0 offset:17408
	v_add_f32_dpp v50, v50, v50 quad_perm:[2,3,0,1] row_mask:0xf bank_mask:0xf bound_ctrl:1
	s_waitcnt lgkmcnt(0)
	v_mul_f32_e32 v53, v29, v53
	v_fmac_f32_e32 v53, v28, v52
	v_fmac_f32_e32 v53, v26, v54
	v_fmac_f32_e32 v53, v27, v55
	v_add_f32_e32 v56, v56, v53
	ds_read_b128 v[52:55], v0 offset:18432
	v_add_f32_dpp v50, v50, v50 row_ror:4 row_mask:0xf bank_mask:0xf bound_ctrl:1
	s_waitcnt lgkmcnt(0)
	v_mul_f32_e32 v53, v25, v53
	v_fmac_f32_e32 v53, v24, v52
	v_fmac_f32_e32 v53, v22, v54
	v_fmac_f32_e32 v53, v23, v55
	v_add_f32_e32 v56, v56, v53
	ds_read_b128 v[52:55], v0 offset:19456
	v_add_f32_dpp v50, v50, v50 row_ror:8 row_mask:0xf bank_mask:0xf bound_ctrl:1
	v_mov_b32_e32 v51, v50
	s_nop 1
	v_permlane16_swap_b32_e32 v50, v51
	s_waitcnt lgkmcnt(0)
	v_mul_f32_e32 v53, v21, v53
	v_fmac_f32_e32 v53, v20, v52
	v_fmac_f32_e32 v53, v18, v54
	v_fmac_f32_e32 v53, v19, v55
	v_add_f32_e32 v52, v56, v53
	ds_read_b128 v[54:57], v0 offset:20480
	v_add_f32_e32 v50, v50, v51
	v_add_f32_dpp v52, v52, v52 quad_perm:[1,0,3,2] row_mask:0xf bank_mask:0xf bound_ctrl:1
	v_mov_b32_e32 v51, v50
	s_nop 1
	v_permlane32_swap_b32_e32 v50, v51
	s_waitcnt lgkmcnt(0)
	v_mul_f32_e32 v55, v33, v55
	v_fmac_f32_e32 v55, v32, v54
	v_fmac_f32_e32 v55, v30, v56
	v_fmac_f32_e32 v55, v31, v57
	v_add_f32_e32 v58, 0, v55
	ds_read_b128 v[54:57], v0 offset:21504
	v_add_f32_dpp v52, v52, v52 quad_perm:[2,3,0,1] row_mask:0xf bank_mask:0xf bound_ctrl:1
	s_waitcnt lgkmcnt(0)
	v_mul_f32_e32 v55, v29, v55
	v_fmac_f32_e32 v55, v28, v54
	v_fmac_f32_e32 v55, v26, v56
	v_fmac_f32_e32 v55, v27, v57
	v_add_f32_e32 v58, v58, v55
	ds_read_b128 v[54:57], v0 offset:22528
	v_add_f32_dpp v52, v52, v52 row_ror:4 row_mask:0xf bank_mask:0xf bound_ctrl:1
	s_waitcnt lgkmcnt(0)
	v_mul_f32_e32 v55, v25, v55
	v_fmac_f32_e32 v55, v24, v54
	v_fmac_f32_e32 v55, v22, v56
	v_fmac_f32_e32 v55, v23, v57
	v_add_f32_e32 v58, v58, v55
	ds_read_b128 v[54:57], v0 offset:23552
	v_add_f32_dpp v52, v52, v52 row_ror:8 row_mask:0xf bank_mask:0xf bound_ctrl:1
	v_mov_b32_e32 v53, v52
	s_nop 1
	v_permlane16_swap_b32_e32 v52, v53
	s_waitcnt lgkmcnt(0)
	v_mul_f32_e32 v55, v21, v55
	v_fmac_f32_e32 v55, v20, v54
	v_fmac_f32_e32 v55, v18, v56
	v_fmac_f32_e32 v55, v19, v57
	v_add_f32_e32 v54, v58, v55
	ds_read_b128 v[56:59], v0 offset:24576
	v_add_f32_e32 v52, v52, v53
	v_add_f32_dpp v54, v54, v54 quad_perm:[1,0,3,2] row_mask:0xf bank_mask:0xf bound_ctrl:1
	v_mov_b32_e32 v53, v52
	s_nop 1
	v_permlane32_swap_b32_e32 v52, v53
	s_waitcnt lgkmcnt(0)
	v_mul_f32_e32 v57, v33, v57
	v_fmac_f32_e32 v57, v32, v56
	v_fmac_f32_e32 v57, v30, v58
	v_fmac_f32_e32 v57, v31, v59
	v_add_f32_e32 v60, 0, v57
	ds_read_b128 v[56:59], v0 offset:25600
	v_add_f32_dpp v54, v54, v54 quad_perm:[2,3,0,1] row_mask:0xf bank_mask:0xf bound_ctrl:1
	s_waitcnt lgkmcnt(0)
	v_mul_f32_e32 v57, v29, v57
	v_fmac_f32_e32 v57, v28, v56
	v_fmac_f32_e32 v57, v26, v58
	v_fmac_f32_e32 v57, v27, v59
	v_add_f32_e32 v60, v60, v57
	ds_read_b128 v[56:59], v0 offset:26624
	v_add_f32_dpp v54, v54, v54 row_ror:4 row_mask:0xf bank_mask:0xf bound_ctrl:1
	s_waitcnt lgkmcnt(0)
	v_mul_f32_e32 v57, v25, v57
	v_fmac_f32_e32 v57, v24, v56
	v_fmac_f32_e32 v57, v22, v58
	v_fmac_f32_e32 v57, v23, v59
	v_add_f32_e32 v60, v60, v57
	ds_read_b128 v[56:59], v0 offset:27648
	v_add_f32_dpp v54, v54, v54 row_ror:8 row_mask:0xf bank_mask:0xf bound_ctrl:1
	v_mov_b32_e32 v55, v54
	s_nop 1
	v_permlane16_swap_b32_e32 v54, v55
	s_waitcnt lgkmcnt(0)
	v_mul_f32_e32 v57, v21, v57
	v_fmac_f32_e32 v57, v20, v56
	v_fmac_f32_e32 v57, v18, v58
	v_fmac_f32_e32 v57, v19, v59
	v_add_f32_e32 v56, v60, v57
	ds_read_b128 v[58:61], v0 offset:28672
	v_add_f32_e32 v54, v54, v55
	v_add_f32_dpp v56, v56, v56 quad_perm:[1,0,3,2] row_mask:0xf bank_mask:0xf bound_ctrl:1
	v_mov_b32_e32 v55, v54
	s_nop 1
	v_permlane32_swap_b32_e32 v54, v55
	s_waitcnt lgkmcnt(0)
	v_mul_f32_e32 v33, v33, v59
	v_fmac_f32_e32 v33, v32, v58
	v_fmac_f32_e32 v33, v30, v60
	v_fmac_f32_e32 v33, v31, v61
	v_add_f32_e32 v58, 0, v33
	ds_read_b128 v[30:33], v0 offset:29696
	v_add_f32_dpp v56, v56, v56 quad_perm:[2,3,0,1] row_mask:0xf bank_mask:0xf bound_ctrl:1
	s_waitcnt lgkmcnt(0)
	v_mul_f32_e32 v29, v29, v31
	v_fmac_f32_e32 v29, v28, v30
	v_fmac_f32_e32 v29, v26, v32
	v_fmac_f32_e32 v29, v27, v33
	v_add_f32_e32 v30, v58, v29
	ds_read_b128 v[26:29], v0 offset:30720
	v_add_f32_dpp v56, v56, v56 row_ror:4 row_mask:0xf bank_mask:0xf bound_ctrl:1
	s_waitcnt lgkmcnt(0)
	v_mul_f32_e32 v25, v25, v27
	v_fmac_f32_e32 v25, v24, v26
	v_fmac_f32_e32 v25, v22, v28
	v_fmac_f32_e32 v25, v23, v29
	v_add_f32_e32 v26, v30, v25
	ds_read_b128 v[22:25], v0 offset:31744
	v_add_f32_dpp v56, v56, v56 row_ror:8 row_mask:0xf bank_mask:0xf bound_ctrl:1
	v_mov_b32_e32 v57, v56
	s_nop 1
	v_permlane16_swap_b32_e32 v56, v57
	s_waitcnt lgkmcnt(0)
	v_mul_f32_e32 v0, v21, v23
	v_fmac_f32_e32 v0, v20, v22
	v_fmac_f32_e32 v0, v18, v24
	v_fmac_f32_e32 v0, v19, v25
	v_add_f32_e32 v0, v26, v0
	v_add_f32_e32 v56, v56, v57
	v_mov_b32_e32 v57, v56
	v_add_f32_dpp v0, v0, v0 quad_perm:[1,0,3,2] row_mask:0xf bank_mask:0xf bound_ctrl:1
	s_nop 0
	v_permlane32_swap_b32_e32 v56, v57
	v_add_f32_dpp v0, v0, v0 quad_perm:[2,3,0,1] row_mask:0xf bank_mask:0xf bound_ctrl:1
	s_nop 1
	v_add_f32_dpp v0, v0, v0 row_ror:4 row_mask:0xf bank_mask:0xf bound_ctrl:1
	s_nop 1
	v_add_f32_dpp v0, v0, v0 row_ror:8 row_mask:0xf bank_mask:0xf bound_ctrl:1
	v_mov_b32_e32 v18, v0
	s_nop 1
	v_permlane16_swap_b32_e32 v0, v18
	v_add_f32_e32 v0, v0, v18
	v_mov_b32_e32 v18, v0
	s_nop 1
	v_permlane32_swap_b32_e32 v0, v18
	s_and_b64 exec, exec, s[4:5]
	s_cbranch_execz .LBB0_478
; DEVI float wave_sum(float v) { v += dpp<0xB1>(v); v += dpp<0x4E>(v); v += dpp<0x124>(v); v += dpp<0x128>(v); return xrow16_sum(v); }
; DEVI void norm_phase(const float* __restrict__ x, const float* __restrict__ gain, bf16_t* __restrict__ out,
;                      const float* wf_src, const float* bf_src, float* logf, char* lds, int wv) {
;     ...
;                     d = wave_sum(d); if (lane == h) z = d; }
;                 if (lane < 8) { z += bf_src[lane]; logf[((size_t)(row >> 14) * 8 + lane) * SEQ + (row & (SEQ - 1))] = fminf(z, 0.f) - __logf(1.f + __expf(-fabsf(z))); }
	global_load_dword v19, v[40:41], off nt
	v_add_f32_e32 v26, v35, v45
	v_add_f32_e32 v25, v46, v47
	v_cndmask_b32_e64 v26, 0, v26, s[20:21]
	v_add_f32_e32 v24, v48, v49
	v_cndmask_b32_e64 v25, v26, v25, s[18:19]
	v_add_f32_e32 v23, v50, v51
	v_cndmask_b32_e64 v24, v25, v24, s[16:17]
	v_add_f32_e32 v22, v52, v53
	v_cndmask_b32_e64 v23, v24, v23, s[14:15]
	v_add_f32_e32 v21, v54, v55
	v_cndmask_b32_e64 v22, v23, v22, s[12:13]
	v_add_f32_e32 v20, v56, v57
	v_cndmask_b32_e64 v21, v22, v21, s[10:11]
	v_add_f32_e32 v0, v0, v18
	v_cndmask_b32_e64 v20, v21, v20, s[8:9]
	v_cndmask_b32_e64 v0, v20, v0, s[6:7]
	s_mov_b32 s22, 0xbfb8aa3b
	v_ashrrev_i32_e32 v18, 14, v44
	v_and_b32_e32 v27, 0x3fff, v44
	s_waitcnt vmcnt(0)
	v_add_f32_e32 v20, v0, v19
	v_mul_f32_e64 v0, |v20|, s22
	v_exp_f32_e32 v21, v0
	s_mov_b32 s22, 0x800000
	v_ashrrev_i32_e32 v19, 31, v18
	v_lshlrev_b64 v[18:19], 19, v[18:19]
	v_add_f32_e32 v21, 1.0, v21
	v_cmp_gt_f32_e32 vcc, s22, v21
	s_mov_b32 s22, 0x3f317217
	v_lshlrev_b32_e32 v0, 2, v27
	v_cndmask_b32_e64 v22, 0, 32, vcc
	v_ldexp_f32 v21, v21, v22
	v_log_f32_e32 v21, v21
	v_mov_b32_e32 v22, 0x41b17218
	v_cndmask_b32_e32 v22, 0, v22, vcc
	v_lshl_add_u64 v[18:19], v[42:43], 0, v[18:19]
	v_mul_f32_e32 v23, 0x3f317217, v21
	v_fma_f32 v23, v21, s22, -v23
	v_fmac_f32_e32 v23, 0x3377d1cf, v21
	s_mov_b32 s22, 0x7f800000
	v_fmac_f32_e32 v23, 0x3f317217, v21
	v_cmp_lt_f32_e64 vcc, |v21|, s22
	v_min_f32_e32 v20, 0, v20
	v_lshl_add_u64 v[18:19], v[18:19], 0, v[0:1]
	v_cndmask_b32_e32 v21, v21, v23, vcc
	v_sub_f32_e32 v21, v21, v22
	v_sub_f32_e32 v20, v20, v21
	flat_store_dword v[18:19], v20
	s_branch .LBB0_478

; DEVI unsigned cvtpk(float lo, float hi) { unsigned r; asm volatile("v_cvt_pk_bf16_f32 %0, %1, %2" : "=v"(r) : "v"(lo), "v"(hi)); return r; }
; DEVI int ltid(int wv) { int t = (wv << 6) | (int)__builtin_amdgcn_mbcnt_hi(~0u, __builtin_amdgcn_mbcnt_lo(~0u, 0u)); asm volatile("" : "+v"(t)); return t; }
; template <int KT, class F> DEVI void cvt_tile(F colptr, int ldsrc, int k0, bf16_t* out, int ldo, int v0, float* tile, int wv) {
;     const int tid = ltid(wv);
;     constexpr int PITCH = KT * 64 + 1;
;     { const int vc = tid & 63, kk = tid >> 6; const float* cp = colptr(v0 + vc) + (size_t)k0 * ldsrc; float v[8 * KT];
; #pragma unroll
;       for (int r = 0; r < 8 * KT; ++r) v[r] = cp[(size_t)(r * 8 + kk) * ldsrc];
; #pragma unroll
;       for (int r = 0; r < 8 * KT; ++r) tile[vc * PITCH + r * 8 + kk] = v[r]; }
;     __syncthreads();
;     { const int vc = tid >> 3, k8 = (tid & 7) * 8;
; #pragma unroll
;       for (int q = 0; q < KT; ++q) { const float* tp = tile + vc * PITCH + q * 64 + k8;
;         u32x4 w = {cvtpk(tp[0], tp[1]), cvtpk(tp[2], tp[3]), cvtpk(tp[4], tp[5]), cvtpk(tp[6], tp[7])};
;         *(u32x4*)(out + (size_t)(v0 + vc) * ldo + k0 + q * 64 + k8) = w; } }
;     __syncthreads();
; }
; DEVI void cvt_ffn_phase(const float* wg, const float* wu, const float* wd, unsigned char* ws, char* lds, int j0, int jstride, int wv) {
;     ...
;     for (int job = j0; job < 352 + 176; job += jstride) {
;         if (job < 352) { const int vt = job >> 2, kg = job & 3; cvt_tile<4>(ColGU{wg, (long)((const char*)wu - (const char*)wg)}, DFF, kg * 256, Wgu, DM, vt * 64, tile, wv); }
;         else { const int j = job - 352, vt = j / 11, kg = j % 11; cvt_tile<4>(ColLin{wd}, DM, kg * 256, Wd, DFF, vt * 64, tile, wv); }
.LBB0_537:
	s_cmpk_gt_i32 s67, 0x15f
	s_mov_b64 s[6:7], -1
	s_cbranch_scc0 .LBB0_539
	s_add_i32 s6, s67, 0xffa0
	s_and_b32 s7, s6, 0xff
	s_mulk_i32 s7, 0x75
	s_lshr_b32 s18, s7, 8
	s_sub_i32 s18, s6, s18
	s_bfe_u32 s18, s18, 0x70001
	s_bfe_u32 s7, s7, 0x80008
	s_add_i32 s18, s18, s7
	s_bfe_u32 s7, s18, 0x50003
	s_mul_i32 s18, s7, 11
	v_mov_b32_e32 v22, v217
	s_sub_i32 s18, s6, s18
	s_lshl_b32 s6, s7, 6
	s_and_b32 s7, s18, 0xff
	v_and_b32_e32 v23, 63, v22
	v_or_b32_e32 v0, s6, v23
	v_ashrrev_i32_e32 v2, 6, v22
	v_lshlrev_b32_e32 v0, 2, v0
	v_lshl_add_u64 v[4:5], s[4:5], 0, v[0:1]
	s_lshl_b32 s46, s7, 20
	v_ashrrev_i32_e32 v3, 31, v2
	v_lshl_add_u64 v[4:5], v[4:5], 0, s[46:47]
	v_lshlrev_b64 v[6:7], 12, v[2:3]
	v_lshl_add_u64 v[4:5], v[4:5], 0, v[6:7]
	v_add_co_u32_e32 v6, vcc, s33, v4
	s_mov_b32 s18, 0x60000
	s_nop 0
	v_addc_co_u32_e32 v7, vcc, 0, v5, vcc
	v_add_co_u32_e32 v8, vcc, s54, v4
	v_lshlrev_b32_e32 v2, 2, v2
	s_nop 0
	v_addc_co_u32_e32 v9, vcc, 0, v5, vcc
	v_add_co_u32_e32 v10, vcc, s27, v4
	s_lshl_b32 s7, s7, 9
	s_nop 0
	v_addc_co_u32_e32 v11, vcc, 0, v5, vcc
	v_add_co_u32_e32 v12, vcc, s38, v4
	s_nop 1
	v_addc_co_u32_e32 v13, vcc, 0, v5, vcc
	v_add_co_u32_e32 v14, vcc, s24, v4
	s_nop 1
	v_addc_co_u32_e32 v15, vcc, 0, v5, vcc
	v_add_co_u32_e32 v16, vcc, s39, v4
	s_nop 1
	v_addc_co_u32_e32 v17, vcc, 0, v5, vcc
	v_add_co_u32_e32 v18, vcc, s25, v4
	s_nop 1
	v_addc_co_u32_e32 v19, vcc, 0, v5, vcc
	global_load_dword v0, v[4:5], off nt
	global_load_dword v3, v[6:7], off nt
	global_load_dword v24, v[8:9], off nt
	global_load_dword v25, v[10:11], off nt
	global_load_dword v26, v[12:13], off nt
	global_load_dword v27, v[14:15], off nt
	global_load_dword v28, v[16:17], off nt
	global_load_dword v29, v[18:19], off nt
	v_add_co_u32_e32 v6, vcc, s23, v4
	s_nop 1
	v_addc_co_u32_e32 v7, vcc, 0, v5, vcc
	v_add_co_u32_e32 v8, vcc, s26, v4
	s_nop 1
	v_addc_co_u32_e32 v9, vcc, 0, v5, vcc
	v_add_co_u32_e32 v10, vcc, s42, v4
	s_nop 1
	v_addc_co_u32_e32 v11, vcc, 0, v5, vcc
	v_add_co_u32_e32 v12, vcc, s57, v4
	s_nop 1
	v_addc_co_u32_e32 v13, vcc, 0, v5, vcc
	v_add_co_u32_e32 v14, vcc, s18, v4
	s_mov_b32 s18, 0x68000
	s_nop 0
	v_addc_co_u32_e32 v15, vcc, 0, v5, vcc
	v_add_co_u32_e32 v16, vcc, s18, v4
	s_mov_b32 s18, 0x70000
	s_nop 0
	v_addc_co_u32_e32 v17, vcc, 0, v5, vcc
	v_add_co_u32_e32 v18, vcc, s18, v4
	s_mov_b32 s18, 0x78000
	s_nop 0
	v_addc_co_u32_e32 v19, vcc, 0, v5, vcc
	v_add_co_u32_e32 v20, vcc, s18, v4
	s_mov_b32 s18, 0x88000
	s_nop 0
	v_addc_co_u32_e32 v21, vcc, 0, v5, vcc
	global_load_dword v30, v[6:7], off nt
	global_load_dword v31, v[8:9], off nt
	global_load_dword v32, v[10:11], off nt
	global_load_dword v33, v[12:13], off nt
	global_load_dword v34, v[14:15], off nt
	global_load_dword v35, v[16:17], off nt
	global_load_dword v36, v[18:19], off nt
	global_load_dword v37, v[20:21], off nt
	v_add_co_u32_e32 v6, vcc, s22, v4
	s_nop 1
	v_addc_co_u32_e32 v7, vcc, 0, v5, vcc
	v_add_co_u32_e32 v8, vcc, s18, v4
	s_mov_b32 s18, 0x90000
	s_nop 0
	v_addc_co_u32_e32 v9, vcc, 0, v5, vcc
	v_add_co_u32_e32 v10, vcc, s18, v4
	s_mov_b32 s18, 0x98000
	s_nop 0
	v_addc_co_u32_e32 v11, vcc, 0, v5, vcc
	v_add_co_u32_e32 v12, vcc, s18, v4
	s_mov_b32 s18, 0xa0000
	s_nop 0
	v_addc_co_u32_e32 v13, vcc, 0, v5, vcc
	v_add_co_u32_e32 v14, vcc, s18, v4
	s_mov_b32 s18, 0xa8000
	s_nop 0
	v_addc_co_u32_e32 v15, vcc, 0, v5, vcc
	v_add_co_u32_e32 v16, vcc, s18, v4
	s_mov_b32 s18, 0xb0000
	s_nop 0
	v_addc_co_u32_e32 v17, vcc, 0, v5, vcc
	v_add_co_u32_e32 v18, vcc, s18, v4
	s_mov_b32 s18, 0xb8000
	s_nop 0
	v_addc_co_u32_e32 v19, vcc, 0, v5, vcc
	v_add_co_u32_e32 v20, vcc, s18, v4
	s_mov_b32 s18, 0xc0000
	s_nop 0
	v_addc_co_u32_e32 v21, vcc, 0, v5, vcc
	global_load_dword v38, v[6:7], off nt
	global_load_dword v39, v[8:9], off nt
	global_load_dword v40, v[10:11], off nt
	global_load_dword v41, v[12:13], off nt
	global_load_dword v42, v[14:15], off nt
	global_load_dword v43, v[16:17], off nt
	global_load_dword v44, v[18:19], off nt
	s_nop 0
	global_load_dword v20, v[20:21], off nt
	v_add_co_u32_e32 v6, vcc, s18, v4
	s_mov_b32 s18, 0xc8000
	s_nop 0
	v_addc_co_u32_e32 v7, vcc, 0, v5, vcc
	v_add_co_u32_e32 v8, vcc, s18, v4
	s_mov_b32 s18, 0xd0000
	s_nop 0
	v_addc_co_u32_e32 v9, vcc, 0, v5, vcc
	v_add_co_u32_e32 v10, vcc, s18, v4
	s_mov_b32 s18, 0xd8000
	s_nop 0
	v_addc_co_u32_e32 v11, vcc, 0, v5, vcc
	v_add_co_u32_e32 v12, vcc, s18, v4
	s_mov_b32 s18, 0xe0000
	s_nop 0
	v_addc_co_u32_e32 v13, vcc, 0, v5, vcc
	v_add_co_u32_e32 v14, vcc, s18, v4
	s_mov_b32 s18, 0xe8000
	s_nop 0
	v_addc_co_u32_e32 v15, vcc, 0, v5, vcc
	v_add_co_u32_e32 v16, vcc, s18, v4
	s_mov_b32 s18, 0xf0000
	s_nop 0
	v_addc_co_u32_e32 v17, vcc, 0, v5, vcc
	v_add_co_u32_e32 v18, vcc, s18, v4
	s_mov_b32 s18, 0xf8000
	s_nop 0
	v_addc_co_u32_e32 v19, vcc, 0, v5, vcc
	v_add_co_u32_e32 v4, vcc, s18, v4
	s_add_u32 s18, s70, s7
	s_nop 0
	v_addc_co_u32_e32 v5, vcc, 0, v5, vcc
	global_load_dword v6, v[6:7], off nt
	s_nop 0
	global_load_dword v7, v[8:9], off nt
	s_nop 0
	global_load_dword v8, v[10:11], off nt
	global_load_dword v9, v[12:13], off nt
	s_nop 0
	global_load_dword v10, v[14:15], off nt
	global_load_dword v11, v[16:17], off nt
	global_load_dword v12, v[18:19], off nt
	s_nop 0
	global_load_dword v4, v[4:5], off nt
	v_mul_u32_u24_e32 v5, 0x404, v23
	v_add3_u32 v2, 0, v5, v2
	v_add_u32_e32 v2, 0x8000, v2
	s_waitcnt vmcnt(0)
	ds_write2_b32 v2, v0, v3 offset1:8
	ds_write2_b32 v2, v24, v25 offset0:16 offset1:24
	ds_write2_b32 v2, v26, v27 offset0:32 offset1:40
	ds_write2_b32 v2, v28, v29 offset0:48 offset1:56
	ds_write2_b32 v2, v30, v31 offset0:64 offset1:72
	ds_write2_b32 v2, v32, v33 offset0:80 offset1:88
	ds_write2_b32 v2, v34, v35 offset0:96 offset1:104
	ds_write2_b32 v2, v36, v37 offset0:112 offset1:120
	ds_write2_b32 v2, v38, v39 offset0:128 offset1:136
	ds_write2_b32 v2, v40, v41 offset0:144 offset1:152
	ds_write2_b32 v2, v42, v43 offset0:160 offset1:168
	ds_write2_b32 v2, v44, v20 offset0:176 offset1:184
	ds_write2_b32 v2, v6, v7 offset0:192 offset1:200
	ds_write2_b32 v2, v8, v9 offset0:208 offset1:216
	ds_write2_b32 v2, v10, v11 offset0:224 offset1:232
	ds_write2_b32 v2, v12, v4 offset0:240 offset1:248
	v_lshlrev_b32_e32 v2, 3, v22
	v_ashrrev_i32_e32 v0, 3, v22
	v_and_b32_e32 v10, 56, v2
	v_mul_lo_u32 v2, v0, s43
	v_lshlrev_b32_e32 v3, 2, v10
	v_add3_u32 v11, 0, v2, v3
	v_add_u32_e32 v2, 0x8000, v11
	s_waitcnt lgkmcnt(0)
	s_barrier
; DEVI unsigned cvtpk(float lo, float hi) { unsigned r; asm volatile("v_cvt_pk_bf16_f32 %0, %1, %2" : "=v"(r) : "v"(lo), "v"(hi)); return r; }
; template <int KT, class F> DEVI void cvt_tile(F colptr, int ldsrc, int k0, bf16_t* out, int ldo, int v0, float* tile, int wv) {
;     ...
;     { const int vc = tid >> 3, k8 = (tid & 7) * 8;
; #pragma unroll
;       for (int q = 0; q < KT; ++q) { const float* tp = tile + vc * PITCH + q * 64 + k8;
;         u32x4 w = {cvtpk(tp[0], tp[1]), cvtpk(tp[2], tp[3]), cvtpk(tp[4], tp[5]), cvtpk(tp[6], tp[7])};
;         *(u32x4*)(out + (size_t)(v0 + vc) * ldo + k0 + q * 64 + k8) = w; } }
;     __syncthreads();
; DEVI void cvt_ffn_phase(const float* wg, const float* wu, const float* wd, unsigned char* ws, char* lds, int j0, int jstride, int wv) {
;     ...
;         if (job < 352) { const int vt = job >> 2, kg = job & 3; cvt_tile<4>(ColGU{wg, (long)((const char*)wu - (const char*)wg)}, DFF, kg * 256, Wgu, DM, vt * 64, tile, wv); }
	ds_read2_b32 v[2:3], v2 offset1:1
	s_waitcnt lgkmcnt(0)
	v_cvt_pk_bf16_f32 v2, v2, v3
	v_add_u32_e32 v3, 0x8008, v11
	ds_read2_b32 v[4:5], v3 offset1:1
	s_addc_u32 s19, s71, 0
	s_waitcnt lgkmcnt(0)
	v_cvt_pk_bf16_f32 v3, v4, v5
	v_add_u32_e32 v4, 0x8010, v11
	v_add_u32_e32 v0, s6, v0
	v_mov_b64_e32 v[6:7], s[18:19]
	ds_read2_b32 v[4:5], v4 offset1:1
	v_mad_i64_i32 v[6:7], s[6:7], v0, s3, v[6:7]
	v_lshlrev_b32_e32 v0, 1, v10
	s_waitcnt lgkmcnt(0)
	v_cvt_pk_bf16_f32 v4, v4, v5
	v_add_u32_e32 v5, 0x8018, v11
	v_lshl_add_u64 v[6:7], v[6:7], 0, v[0:1]
	ds_read2_b32 v[8:9], v5 offset1:1
	s_waitcnt lgkmcnt(0)
	v_cvt_pk_bf16_f32 v5, v8, v9
	flat_store_dwordx4 v[6:7], v[2:5]
	v_add_u32_e32 v0, 0x8100, v11
	ds_read2_b32 v[2:3], v0 offset1:1
	v_add_u32_e32 v0, 0x8108, v11
	s_waitcnt lgkmcnt(0)
	v_cvt_pk_bf16_f32 v2, v2, v3
	ds_read2_b32 v[4:5], v0 offset1:1
	v_add_u32_e32 v0, 0x8110, v11
	s_waitcnt lgkmcnt(0)
	v_cvt_pk_bf16_f32 v3, v4, v5
	ds_read2_b32 v[4:5], v0 offset1:1
	v_add_u32_e32 v0, 0x8118, v11
	s_waitcnt lgkmcnt(0)
	v_cvt_pk_bf16_f32 v4, v4, v5
	ds_read2_b32 v[8:9], v0 offset1:1
	s_waitcnt lgkmcnt(0)
	v_cvt_pk_bf16_f32 v5, v8, v9
	flat_store_dwordx4 v[6:7], v[2:5] offset:128
	v_add_u32_e32 v0, 0x8200, v11
	ds_read2_b32 v[2:3], v0 offset1:1
	v_add_u32_e32 v0, 0x8208, v11
	s_waitcnt lgkmcnt(0)
	v_cvt_pk_bf16_f32 v2, v2, v3
	ds_read2_b32 v[4:5], v0 offset1:1
	v_add_u32_e32 v0, 0x8210, v11
	s_waitcnt lgkmcnt(0)
	v_cvt_pk_bf16_f32 v3, v4, v5
	ds_read2_b32 v[4:5], v0 offset1:1
	v_add_u32_e32 v0, 0x8218, v11
	s_waitcnt lgkmcnt(0)
	v_cvt_pk_bf16_f32 v4, v4, v5
	ds_read2_b32 v[8:9], v0 offset1:1
	s_waitcnt lgkmcnt(0)
	v_cvt_pk_bf16_f32 v5, v8, v9
	flat_store_dwordx4 v[6:7], v[2:5] offset:256
	v_add_u32_e32 v0, 0x8300, v11
	ds_read2_b32 v[2:3], v0 offset1:1
	v_add_u32_e32 v0, 0x8308, v11
	s_waitcnt lgkmcnt(0)
	v_cvt_pk_bf16_f32 v2, v2, v3
	ds_read2_b32 v[4:5], v0 offset1:1
	v_add_u32_e32 v0, 0x8310, v11
	s_waitcnt lgkmcnt(0)
	v_cvt_pk_bf16_f32 v3, v4, v5
	ds_read2_b32 v[4:5], v0 offset1:1
	v_add_u32_e32 v0, 0x8318, v11
	s_waitcnt lgkmcnt(0)
	v_cvt_pk_bf16_f32 v4, v4, v5
	ds_read2_b32 v[8:9], v0 offset1:1
	s_waitcnt lgkmcnt(0)
	v_cvt_pk_bf16_f32 v5, v8, v9
	flat_store_dwordx4 v[6:7], v[2:5] offset:384
	s_waitcnt lgkmcnt(0)
	s_barrier
	s_mov_b64 s[6:7], 0
.LBB0_539:
	s_andn2_b64 vcc, exec, s[6:7]
	s_cbranch_vccnz .LBB0_536
	s_and_b32 s7, s12, 0x300
	s_and_b32 s6, s14, 0xffffffc0
	s_bitcmp1_b32 s67, 3
	s_cselect_b32 s19, s10, 0
	s_cselect_b32 s18, s11, 0
	s_add_u32 s20, s8, s19
	s_addc_u32 s21, s9, s18
	s_and_b32 s18, s16, 0xffffff80
	v_mov_b32_e32 v20, v217
	s_ashr_i32 s19, s18, 31
	s_lshl_b64 s[18:19], s[18:19], 2
	v_and_b32_e32 v21, 63, v20
	s_add_u32 s18, s20, s18
	v_and_or_b32 v0, s14, 64, v21
	s_addc_u32 s19, s21, s19
	v_lshlrev_b32_e32 v0, 2, v0
	v_ashrrev_i32_e32 v22, 6, v20
	v_lshl_add_u64 v[2:3], s[18:19], 0, v[0:1]
	s_mul_i32 s46, s7, 0x2c00
	v_lshl_add_u64 v[2:3], v[2:3], 0, s[46:47]
	v_add_u32_e32 v0, 8, v22
	v_mad_i64_i32 v[6:7], s[18:19], v0, s44, v[2:3]
	v_add_u32_e32 v0, 16, v22
	v_mad_i64_i32 v[8:9], s[18:19], v0, s44, v[2:3]
	v_add_u32_e32 v0, 24, v22
	v_mad_i64_i32 v[10:11], s[18:19], v0, s44, v[2:3]
	v_add_u32_e32 v0, 32, v22
	v_mad_i64_i32 v[12:13], s[18:19], v0, s44, v[2:3]
	v_add_u32_e32 v0, 40, v22
	v_mad_i64_i32 v[14:15], s[18:19], v0, s44, v[2:3]
	v_add_u32_e32 v0, 48, v22
	v_mad_i64_i32 v[16:17], s[18:19], v0, s44, v[2:3]
	v_add_u32_e32 v0, 56, v22
	v_mad_i64_i32 v[4:5], s[18:19], v22, s44, v[2:3]
	v_mad_i64_i32 v[18:19], s[18:19], v0, s44, v[2:3]
	global_load_dword v0, v[4:5], off nt
	global_load_dword v23, v[6:7], off nt
	global_load_dword v24, v[8:9], off nt
	global_load_dword v25, v[10:11], off nt
	global_load_dword v26, v[12:13], off nt
	global_load_dword v27, v[14:15], off nt
	global_load_dword v28, v[16:17], off nt
	global_load_dword v29, v[18:19], off nt
	v_add_u32_e32 v4, 64, v22
	v_add_u32_e32 v6, 0x48, v22
	v_add_u32_e32 v8, 0x50, v22
	v_add_u32_e32 v10, 0x58, v22
	v_add_u32_e32 v12, 0x60, v22
	v_add_u32_e32 v14, 0x68, v22
	v_add_u32_e32 v16, 0x70, v22
	v_add_u32_e32 v18, 0x78, v22
	v_mad_i64_i32 v[4:5], s[18:19], v4, s44, v[2:3]
	v_mad_i64_i32 v[6:7], s[18:19], v6, s44, v[2:3]
	v_mad_i64_i32 v[8:9], s[18:19], v8, s44, v[2:3]
	v_mad_i64_i32 v[10:11], s[18:19], v10, s44, v[2:3]
	v_mad_i64_i32 v[12:13], s[18:19], v12, s44, v[2:3]
	v_mad_i64_i32 v[14:15], s[18:19], v14, s44, v[2:3]
	v_mad_i64_i32 v[16:17], s[18:19], v16, s44, v[2:3]
	v_mad_i64_i32 v[18:19], s[18:19], v18, s44, v[2:3]
	global_load_dword v30, v[4:5], off nt
	global_load_dword v31, v[6:7], off nt
	global_load_dword v32, v[8:9], off nt
	global_load_dword v33, v[10:11], off nt
	global_load_dword v34, v[12:13], off nt
	global_load_dword v35, v[14:15], off nt
	global_load_dword v36, v[16:17], off nt
	global_load_dword v37, v[18:19], off nt
	v_add_u32_e32 v4, 0x80, v22
	v_add_u32_e32 v6, 0x88, v22
	v_add_u32_e32 v8, 0x90, v22
	v_add_u32_e32 v10, 0x98, v22
	v_add_u32_e32 v12, 0xa0, v22
	v_add_u32_e32 v14, 0xa8, v22
	v_add_u32_e32 v16, 0xb0, v22
	v_add_u32_e32 v18, 0xb8, v22
	v_mad_i64_i32 v[4:5], s[18:19], v4, s44, v[2:3]
	v_mad_i64_i32 v[6:7], s[18:19], v6, s44, v[2:3]
	v_mad_i64_i32 v[8:9], s[18:19], v8, s44, v[2:3]
	v_mad_i64_i32 v[10:11], s[18:19], v10, s44, v[2:3]
	v_mad_i64_i32 v[12:13], s[18:19], v12, s44, v[2:3]
	v_mad_i64_i32 v[14:15], s[18:19], v14, s44, v[2:3]
	v_mad_i64_i32 v[16:17], s[18:19], v16, s44, v[2:3]
	v_mad_i64_i32 v[18:19], s[18:19], v18, s44, v[2:3]
	global_load_dword v38, v[4:5], off nt
	global_load_dword v39, v[6:7], off nt
	global_load_dword v40, v[8:9], off nt
	global_load_dword v41, v[10:11], off nt
	global_load_dword v42, v[12:13], off nt
	global_load_dword v43, v[14:15], off nt
	global_load_dword v44, v[16:17], off nt
	s_nop 0
	global_load_dword v18, v[18:19], off nt
	v_add_u32_e32 v4, 0xc0, v22
	v_add_u32_e32 v6, 0xc8, v22
	v_add_u32_e32 v8, 0xd0, v22
	v_add_u32_e32 v10, 0xd8, v22
	v_add_u32_e32 v12, 0xe0, v22
	v_add_u32_e32 v14, 0xe8, v22
	v_add_u32_e32 v16, 0xf0, v22
	v_add_u32_e32 v19, 0xf8, v22
	v_mad_i64_i32 v[4:5], s[18:19], v4, s44, v[2:3]
	v_mad_i64_i32 v[6:7], s[18:19], v6, s44, v[2:3]
	v_mad_i64_i32 v[8:9], s[18:19], v8, s44, v[2:3]
	v_mad_i64_i32 v[10:11], s[18:19], v10, s44, v[2:3]
	v_mad_i64_i32 v[12:13], s[18:19], v12, s44, v[2:3]
	v_mad_i64_i32 v[14:15], s[18:19], v14, s44, v[2:3]
	v_mad_i64_i32 v[16:17], s[18:19], v16, s44, v[2:3]
	v_mad_i64_i32 v[2:3], s[18:19], v19, s44, v[2:3]
	global_load_dword v4, v[4:5], off nt
	s_nop 0
	global_load_dword v5, v[6:7], off nt
	s_nop 0
	global_load_dword v6, v[8:9], off nt
	global_load_dword v7, v[10:11], off nt
	s_nop 0
	global_load_dword v8, v[12:13], off nt
	global_load_dword v9, v[14:15], off nt
	global_load_dword v10, v[16:17], off nt
	s_nop 0
	global_load_dword v2, v[2:3], off nt
	v_mul_u32_u24_e32 v3, 0x404, v21
	v_lshlrev_b32_e32 v11, 2, v22
	v_add3_u32 v3, 0, v3, v11
	v_add_u32_e32 v3, 0x8000, v3
	s_waitcnt vmcnt(0)
; DEVI unsigned cvtpk(float lo, float hi) { unsigned r; asm volatile("v_cvt_pk_bf16_f32 %0, %1, %2" : "=v"(r) : "v"(lo), "v"(hi)); return r; }
; template <int KT, class F> DEVI void cvt_tile(F colptr, int ldsrc, int k0, bf16_t* out, int ldo, int v0, float* tile, int wv) {
;     ...
; #pragma unroll
;       for (int r = 0; r < 8 * KT; ++r) tile[vc * PITCH + r * 8 + kk] = v[r]; }
;     __syncthreads();
;     { const int vc = tid >> 3, k8 = (tid & 7) * 8;
; #pragma unroll
;       for (int q = 0; q < KT; ++q) { const float* tp = tile + vc * PITCH + q * 64 + k8;
;         u32x4 w = {cvtpk(tp[0], tp[1]), cvtpk(tp[2], tp[3]), cvtpk(tp[4], tp[5]), cvtpk(tp[6], tp[7])};
;         *(u32x4*)(out + (size_t)(v0 + vc) * ldo + k0 + q * 64 + k8) = w; } }
;     __syncthreads();
	ds_write2_b32 v3, v0, v23 offset1:8
	ds_write2_b32 v3, v24, v25 offset0:16 offset1:24
	ds_write2_b32 v3, v26, v27 offset0:32 offset1:40
	ds_write2_b32 v3, v28, v29 offset0:48 offset1:56
	ds_write2_b32 v3, v30, v31 offset0:64 offset1:72
	ds_write2_b32 v3, v32, v33 offset0:80 offset1:88
	ds_write2_b32 v3, v34, v35 offset0:96 offset1:104
	ds_write2_b32 v3, v36, v37 offset0:112 offset1:120
	ds_write2_b32 v3, v38, v39 offset0:128 offset1:136
	ds_write2_b32 v3, v40, v41 offset0:144 offset1:152
	ds_write2_b32 v3, v42, v43 offset0:160 offset1:168
	ds_write2_b32 v3, v44, v18 offset0:176 offset1:184
	ds_write2_b32 v3, v4, v5 offset0:192 offset1:200
	ds_write2_b32 v3, v6, v7 offset0:208 offset1:216
	ds_write2_b32 v3, v8, v9 offset0:224 offset1:232
	ds_write2_b32 v3, v10, v2 offset0:240 offset1:248
	v_lshlrev_b32_e32 v2, 3, v20
	v_ashrrev_i32_e32 v0, 3, v20
	v_and_b32_e32 v10, 56, v2
	v_mul_lo_u32 v2, v0, s43
	v_lshlrev_b32_e32 v3, 2, v10
	v_add3_u32 v11, 0, v2, v3
	v_add_u32_e32 v2, 0x8000, v11
	s_waitcnt lgkmcnt(0)
	s_barrier
	ds_read2_b32 v[2:3], v2 offset1:1
	s_waitcnt lgkmcnt(0)
	v_cvt_pk_bf16_f32 v2, v2, v3
	v_add_u32_e32 v3, 0x8008, v11
	ds_read2_b32 v[4:5], v3 offset1:1
	s_lshl_b32 s7, s7, 1
	v_add_u32_e32 v6, s6, v0
	s_waitcnt lgkmcnt(0)
	v_cvt_pk_bf16_f32 v3, v4, v5
	v_add_u32_e32 v4, 0x8010, v11
	s_add_u32 s18, s72, s7
	v_ashrrev_i32_e32 v7, 31, v6
	ds_read2_b32 v[4:5], v4 offset1:1
	s_addc_u32 s19, s73, 0
	v_add_u32_e32 v0, 0x8018, v11
	v_lshlrev_b64 v[6:7], 11, v[6:7]
	s_waitcnt lgkmcnt(0)
	v_cvt_pk_bf16_f32 v4, v4, v5
	ds_read2_b32 v[8:9], v0 offset1:1
	v_lshl_add_u64 v[6:7], s[18:19], 0, v[6:7]
	v_lshlrev_b32_e32 v0, 1, v10
	v_lshl_add_u64 v[6:7], v[6:7], 0, v[0:1]
	s_waitcnt lgkmcnt(0)
	v_cvt_pk_bf16_f32 v5, v8, v9
	flat_store_dwordx4 v[6:7], v[2:5]
	v_add_u32_e32 v0, 0x8100, v11
	ds_read2_b32 v[2:3], v0 offset1:1
	v_add_u32_e32 v0, 0x8108, v11
	s_waitcnt lgkmcnt(0)
	v_cvt_pk_bf16_f32 v2, v2, v3
	ds_read2_b32 v[4:5], v0 offset1:1
	v_add_u32_e32 v0, 0x8110, v11
	s_waitcnt lgkmcnt(0)
	v_cvt_pk_bf16_f32 v3, v4, v5
	ds_read2_b32 v[4:5], v0 offset1:1
	v_add_u32_e32 v0, 0x8118, v11
	s_waitcnt lgkmcnt(0)
	v_cvt_pk_bf16_f32 v4, v4, v5
	ds_read2_b32 v[8:9], v0 offset1:1
	s_waitcnt lgkmcnt(0)
	v_cvt_pk_bf16_f32 v5, v8, v9
	flat_store_dwordx4 v[6:7], v[2:5] offset:128
	v_add_u32_e32 v0, 0x8200, v11
	ds_read2_b32 v[2:3], v0 offset1:1
	v_add_u32_e32 v0, 0x8208, v11
	s_waitcnt lgkmcnt(0)
	v_cvt_pk_bf16_f32 v2, v2, v3
	ds_read2_b32 v[4:5], v0 offset1:1
	v_add_u32_e32 v0, 0x8210, v11
	s_waitcnt lgkmcnt(0)
	v_cvt_pk_bf16_f32 v3, v4, v5
	ds_read2_b32 v[4:5], v0 offset1:1
	v_add_u32_e32 v0, 0x8218, v11
	s_waitcnt lgkmcnt(0)
	v_cvt_pk_bf16_f32 v4, v4, v5
	ds_read2_b32 v[8:9], v0 offset1:1
	s_waitcnt lgkmcnt(0)
	v_cvt_pk_bf16_f32 v5, v8, v9
	flat_store_dwordx4 v[6:7], v[2:5] offset:256
	v_add_u32_e32 v0, 0x8300, v11
	ds_read2_b32 v[2:3], v0 offset1:1
	v_add_u32_e32 v0, 0x8308, v11
	s_waitcnt lgkmcnt(0)
	v_cvt_pk_bf16_f32 v2, v2, v3
	ds_read2_b32 v[4:5], v0 offset1:1
	v_add_u32_e32 v0, 0x8310, v11
	s_waitcnt lgkmcnt(0)
	v_cvt_pk_bf16_f32 v3, v4, v5
	ds_read2_b32 v[4:5], v0 offset1:1
	v_add_u32_e32 v0, 0x8318, v11
	s_waitcnt lgkmcnt(0)
	v_cvt_pk_bf16_f32 v4, v4, v5
	ds_read2_b32 v[8:9], v0 offset1:1
	s_waitcnt lgkmcnt(0)
	v_cvt_pk_bf16_f32 v5, v8, v9
	flat_store_dwordx4 v[6:7], v[2:5] offset:384
	s_waitcnt lgkmcnt(0)
	s_barrier
	s_branch .LBB0_536
